# GEMM K-loop first iteration peeled with inline-zero SrcC (no accumulator zeroing), on top of de-serialized epilogue and norm loops
# speedup vs baseline: 1.0218x; 1.0066x over previous
.LBB0_242:
	s_ashr_i32 s11, s10, 31
	s_xor_b64 s[14:15], s[28:29], -1
	s_lshl_b64 s[12:13], s[10:11], 20
	s_add_u32 s12, s34, s12
	s_addc_u32 s13, s35, s13
	s_and_b64 s[16:17], s[28:29], exec
	s_cselect_b32 s11, s13, s19
	s_cselect_b32 s67, s12, s18
	s_ashr_i32 s9, s8, 31
	s_lshl_b64 s[16:17], s[8:9], 20
	s_add_u32 s16, s22, s16
	s_addc_u32 s17, s23, s17
	s_and_b64 s[28:29], s[28:29], exec
	s_cselect_b32 s9, s17, s37
	s_cselect_b32 s28, s16, s36
	s_add_u32 s18, s18, 0x80080
	s_addc_u32 s19, s19, 0
	s_add_u32 s29, s36, 0x100
	s_addc_u32 s72, s37, 0
	s_mov_b32 s73, -2
	ds_read_b128 v[150:153], v146
	ds_read_b128 v[154:157], v146 offset:1024
	ds_read_b128 v[158:161], v146 offset:2048
	ds_read_b128 v[162:165], v146 offset:3072
	s_add_u32 s36, s18, 0xfff80080
	s_addc_u32 s37, s19, -1
	s_cmp_eq_u32 s73, 28
	s_cselect_b32 s55, s11, s37
	s_cselect_b32 s54, s67, s36
	s_cselect_b32 s37, s9, s72
	s_cselect_b32 s36, s28, s29
	v_lshl_add_u64 v[198:199], s[18:19], 0, v[138:139]
	s_add_i32 m0, s56, 0xc000
	ds_read_b128 v[166:169], v147
	ds_read_b128 v[170:173], v147 offset:1024
	ds_read_b128 v[174:177], v147 offset:2048
	ds_read_b128 v[178:181], v147 offset:3072
	ds_read_b128 v[182:185], v147 offset:4096
	ds_read_b128 v[186:189], v147 offset:5120
	ds_read_b128 v[190:193], v147 offset:6144
	ds_read_b128 v[194:197], v147 offset:7168
	global_load_lds_dwordx4 v[198:199], off
	v_lshl_add_u64 v[198:199], s[18:19], 0, v[140:141]
	s_add_i32 m0, s56, 0xe000
	s_nop 0
	global_load_lds_dwordx4 v[198:199], off
	s_waitcnt lgkmcnt(8)
	s_barrier
	s_waitcnt lgkmcnt(0)
	s_setprio 1
	s_waitcnt lgkmcnt(0)
	v_mfma_f32_16x16x32_bf16 v[124:127], v[150:153], v[166:169], 0
	v_mfma_f32_16x16x32_bf16 v[120:123], v[158:161], v[166:169], 0
	v_mfma_f32_16x16x32_bf16 v[116:119], v[150:153], v[174:177], 0
	v_mfma_f32_16x16x32_bf16 v[108:111], v[158:161], v[174:177], 0
	v_mfma_f32_16x16x32_bf16 v[100:103], v[150:153], v[182:185], 0
	v_mfma_f32_16x16x32_bf16 v[96:99], v[158:161], v[182:185], 0
	v_mfma_f32_16x16x32_bf16 v[84:87], v[150:153], v[190:193], 0
	v_mfma_f32_16x16x32_bf16 v[80:83], v[158:161], v[190:193], 0
	v_mfma_f32_16x16x32_bf16 v[124:127], v[154:157], v[170:173], v[124:127]
	v_mfma_f32_16x16x32_bf16 v[120:123], v[162:165], v[170:173], v[120:123]
	v_mfma_f32_16x16x32_bf16 v[116:119], v[154:157], v[178:181], v[116:119]
	v_mfma_f32_16x16x32_bf16 v[108:111], v[162:165], v[178:181], v[108:111]
	v_mfma_f32_16x16x32_bf16 v[100:103], v[154:157], v[186:189], v[100:103]
	v_mfma_f32_16x16x32_bf16 v[96:99], v[162:165], v[186:189], v[96:99]
	v_mfma_f32_16x16x32_bf16 v[84:87], v[154:157], v[194:197], v[84:87]
	v_mfma_f32_16x16x32_bf16 v[80:83], v[162:165], v[194:197], v[80:83]
	s_setprio 0
	s_barrier
	s_add_i32 s74, s63, s33
	v_lshl_add_u64 v[214:215], s[36:37], 0, v[130:131]
	s_mov_b32 m0, s74
	ds_read_b128 v[198:201], v148
	ds_read_b128 v[202:205], v148 offset:1024
	ds_read_b128 v[206:209], v148 offset:2048
	ds_read_b128 v[210:213], v148 offset:3072
	global_load_lds_dwordx4 v[214:215], off
	v_lshl_add_u64 v[216:217], s[36:37], 0, v[134:135]
	s_add_i32 m0, s74, 0x2000
	s_nop 0
	global_load_lds_dwordx4 v[216:217], off
	s_barrier
	s_waitcnt lgkmcnt(0)
	s_setprio 1
	s_waitcnt lgkmcnt(0)
	v_mfma_f32_16x16x32_bf16 v[112:115], v[198:201], v[166:169], 0
	v_mfma_f32_16x16x32_bf16 v[104:107], v[206:209], v[166:169], 0
	v_mfma_f32_16x16x32_bf16 v[92:95], v[198:201], v[174:177], 0
	v_mfma_f32_16x16x32_bf16 v[88:91], v[206:209], v[174:177], 0
	v_mfma_f32_16x16x32_bf16 v[76:79], v[198:201], v[182:185], 0
	v_mfma_f32_16x16x32_bf16 v[72:75], v[206:209], v[182:185], 0
	v_mfma_f32_16x16x32_bf16 v[68:71], v[198:201], v[190:193], 0
	v_mfma_f32_16x16x32_bf16 v[64:67], v[206:209], v[190:193], 0
	v_mfma_f32_16x16x32_bf16 v[112:115], v[202:205], v[170:173], v[112:115]
	v_mfma_f32_16x16x32_bf16 v[104:107], v[210:213], v[170:173], v[104:107]
	v_mfma_f32_16x16x32_bf16 v[92:95], v[202:205], v[178:181], v[92:95]
	v_mfma_f32_16x16x32_bf16 v[88:91], v[210:213], v[178:181], v[88:91]
	v_mfma_f32_16x16x32_bf16 v[76:79], v[202:205], v[186:189], v[76:79]
	v_mfma_f32_16x16x32_bf16 v[72:75], v[210:213], v[186:189], v[72:75]
	v_mfma_f32_16x16x32_bf16 v[68:71], v[202:205], v[194:197], v[68:71]
	v_mfma_f32_16x16x32_bf16 v[64:67], v[210:213], v[194:197], v[64:67]
	s_setprio 0
	s_mov_b32 m0, s56
	v_lshl_add_u64 v[218:219], s[54:55], 0, v[128:129]
	s_barrier
	ds_read_b128 v[166:169], v147 offset:16384
	ds_read_b128 v[170:173], v147 offset:17408
	ds_read_b128 v[174:177], v147 offset:18432
	ds_read_b128 v[178:181], v147 offset:19456
	ds_read_b128 v[182:185], v147 offset:20480
	ds_read_b128 v[186:189], v147 offset:21504
	ds_read_b128 v[190:193], v147 offset:22528
	ds_read_b128 v[194:197], v147 offset:23552
	global_load_lds_dwordx4 v[218:219], off
	v_lshl_add_u64 v[220:221], s[54:55], 0, v[132:133]
	s_mov_b32 m0, s57
	s_nop 0
	global_load_lds_dwordx4 v[220:221], off
	s_barrier
	s_waitcnt lgkmcnt(0)
	s_setprio 1
	s_waitcnt lgkmcnt(0)
	v_mfma_f32_16x16x32_bf16 v[60:63], v[150:153], v[166:169], 0
	v_mfma_f32_16x16x32_bf16 v[56:59], v[158:161], v[166:169], 0
	v_mfma_f32_16x16x32_bf16 v[52:55], v[150:153], v[174:177], 0
	v_mfma_f32_16x16x32_bf16 v[48:51], v[158:161], v[174:177], 0
	v_mfma_f32_16x16x32_bf16 v[36:39], v[150:153], v[182:185], 0
	v_mfma_f32_16x16x32_bf16 v[32:35], v[158:161], v[182:185], 0
	v_mfma_f32_16x16x32_bf16 v[20:23], v[150:153], v[190:193], 0
	v_mfma_f32_16x16x32_bf16 v[16:19], v[158:161], v[190:193], 0
	v_mfma_f32_16x16x32_bf16 v[60:63], v[154:157], v[170:173], v[60:63]
	v_mfma_f32_16x16x32_bf16 v[56:59], v[162:165], v[170:173], v[56:59]
	v_mfma_f32_16x16x32_bf16 v[52:55], v[154:157], v[178:181], v[52:55]
	v_mfma_f32_16x16x32_bf16 v[48:51], v[162:165], v[178:181], v[48:51]
	v_mfma_f32_16x16x32_bf16 v[36:39], v[154:157], v[186:189], v[36:39]
	v_mfma_f32_16x16x32_bf16 v[32:35], v[162:165], v[186:189], v[32:35]
	v_mfma_f32_16x16x32_bf16 v[20:23], v[154:157], v[194:197], v[20:23]
	v_mfma_f32_16x16x32_bf16 v[16:19], v[162:165], v[194:197], v[16:19]
	s_setprio 0
	s_barrier
	s_add_u32 s74, s36, 0x80000
	s_addc_u32 s75, s37, 0
	s_add_i32 s76, s64, s33
	v_lshl_add_u64 v[150:151], s[74:75], 0, v[130:131]
	s_mov_b32 m0, s76
	s_nop 0
	global_load_lds_dwordx4 v[150:151], off
	v_lshl_add_u64 v[150:151], s[74:75], 0, v[134:135]
	s_add_i32 m0, s76, 0x2000
	s_nop 0
	global_load_lds_dwordx4 v[150:151], off
	s_waitcnt vmcnt(6)
	s_barrier
	s_setprio 1
	v_mfma_f32_16x16x32_bf16 v[44:47], v[198:201], v[166:169], 0
	v_mfma_f32_16x16x32_bf16 v[40:43], v[206:209], v[166:169], 0
	v_mfma_f32_16x16x32_bf16 v[28:31], v[198:201], v[174:177], 0
	v_mfma_f32_16x16x32_bf16 v[24:27], v[206:209], v[174:177], 0
	v_mfma_f32_16x16x32_bf16 v[12:15], v[198:201], v[182:185], 0
	v_mfma_f32_16x16x32_bf16 v[8:11], v[206:209], v[182:185], 0
	v_mfma_f32_16x16x32_bf16 v[4:7], v[198:201], v[190:193], 0
	v_mfma_f32_16x16x32_bf16 v[0:3], v[206:209], v[190:193], 0
	v_mfma_f32_16x16x32_bf16 v[44:47], v[202:205], v[170:173], v[44:47]
	v_mfma_f32_16x16x32_bf16 v[40:43], v[210:213], v[170:173], v[40:43]
	v_mfma_f32_16x16x32_bf16 v[28:31], v[202:205], v[178:181], v[28:31]
	v_mfma_f32_16x16x32_bf16 v[24:27], v[210:213], v[178:181], v[24:27]
	v_mfma_f32_16x16x32_bf16 v[12:15], v[202:205], v[186:189], v[12:15]
	v_mfma_f32_16x16x32_bf16 v[8:11], v[210:213], v[186:189], v[8:11]
	v_mfma_f32_16x16x32_bf16 v[4:7], v[202:205], v[194:197], v[4:7]
	v_mfma_f32_16x16x32_bf16 v[0:3], v[210:213], v[194:197], v[0:3]
	s_setprio 0
	s_add_i32 s74, 0, 0x18000
	v_add_u32_e32 v149, s74, v143
	s_barrier
	ds_read_b128 v[150:153], v149
	ds_read_b128 v[154:157], v149 offset:1024
	ds_read_b128 v[158:161], v149 offset:2048
	ds_read_b128 v[162:165], v149 offset:3072
	s_add_u32 s54, s54, 0x80000
	s_addc_u32 s55, s55, 0
	s_mov_b32 m0, s58
	v_lshl_add_u64 v[198:199], s[54:55], 0, v[128:129]
	ds_read_b128 v[166:169], v147 offset:32768
	ds_read_b128 v[170:173], v147 offset:33792
	ds_read_b128 v[174:177], v147 offset:34816
	ds_read_b128 v[178:181], v147 offset:35840
	ds_read_b128 v[182:185], v147 offset:36864
	ds_read_b128 v[186:189], v147 offset:37888
	ds_read_b128 v[190:193], v147 offset:38912
	ds_read_b128 v[194:197], v147 offset:39936
	global_load_lds_dwordx4 v[198:199], off
	v_lshl_add_u64 v[198:199], s[54:55], 0, v[132:133]
	s_mov_b32 m0, s59
	s_nop 0
	global_load_lds_dwordx4 v[198:199], off
	s_waitcnt lgkmcnt(8)
	s_barrier
	s_waitcnt lgkmcnt(0)
	s_setprio 1
	s_waitcnt lgkmcnt(0)
	v_mfma_f32_16x16x32_bf16 v[124:127], v[150:153], v[166:169], v[124:127]
	v_mfma_f32_16x16x32_bf16 v[120:123], v[158:161], v[166:169], v[120:123]
	v_mfma_f32_16x16x32_bf16 v[116:119], v[150:153], v[174:177], v[116:119]
	v_mfma_f32_16x16x32_bf16 v[108:111], v[158:161], v[174:177], v[108:111]
	v_mfma_f32_16x16x32_bf16 v[100:103], v[150:153], v[182:185], v[100:103]
	v_mfma_f32_16x16x32_bf16 v[96:99], v[158:161], v[182:185], v[96:99]
	v_mfma_f32_16x16x32_bf16 v[84:87], v[150:153], v[190:193], v[84:87]
	v_mfma_f32_16x16x32_bf16 v[80:83], v[158:161], v[190:193], v[80:83]
	v_mfma_f32_16x16x32_bf16 v[124:127], v[154:157], v[170:173], v[124:127]
	v_mfma_f32_16x16x32_bf16 v[120:123], v[162:165], v[170:173], v[120:123]
	v_mfma_f32_16x16x32_bf16 v[116:119], v[154:157], v[178:181], v[116:119]
	v_mfma_f32_16x16x32_bf16 v[108:111], v[162:165], v[178:181], v[108:111]
	v_mfma_f32_16x16x32_bf16 v[100:103], v[154:157], v[186:189], v[100:103]
	v_mfma_f32_16x16x32_bf16 v[96:99], v[162:165], v[186:189], v[96:99]
	v_mfma_f32_16x16x32_bf16 v[84:87], v[154:157], v[194:197], v[84:87]
	v_mfma_f32_16x16x32_bf16 v[80:83], v[162:165], v[194:197], v[80:83]
	s_setprio 0
	s_barrier
	s_add_i32 s54, 0, 0x1c000
	s_add_i32 s55, s74, s33
	v_add_u32_e32 v149, s54, v143
	v_lshl_add_u64 v[214:215], v[214:215], 0, s[6:7]
	s_mov_b32 m0, s55
	ds_read_b128 v[198:201], v149
	ds_read_b128 v[202:205], v149 offset:1024
	ds_read_b128 v[206:209], v149 offset:2048
	ds_read_b128 v[210:213], v149 offset:3072
	global_load_lds_dwordx4 v[214:215], off
	v_lshl_add_u64 v[214:215], v[216:217], 0, s[6:7]
	s_add_i32 m0, s55, 0x2000
	s_nop 0
	global_load_lds_dwordx4 v[214:215], off
	s_barrier
	s_waitcnt lgkmcnt(0)
	s_setprio 1
	s_waitcnt lgkmcnt(0)
	v_mfma_f32_16x16x32_bf16 v[112:115], v[198:201], v[166:169], v[112:115]
	v_mfma_f32_16x16x32_bf16 v[104:107], v[206:209], v[166:169], v[104:107]
	v_mfma_f32_16x16x32_bf16 v[92:95], v[198:201], v[174:177], v[92:95]
	v_mfma_f32_16x16x32_bf16 v[88:91], v[206:209], v[174:177], v[88:91]
	v_mfma_f32_16x16x32_bf16 v[76:79], v[198:201], v[182:185], v[76:79]
	v_mfma_f32_16x16x32_bf16 v[72:75], v[206:209], v[182:185], v[72:75]
	v_mfma_f32_16x16x32_bf16 v[68:71], v[198:201], v[190:193], v[68:71]
	v_mfma_f32_16x16x32_bf16 v[64:67], v[206:209], v[190:193], v[64:67]
	v_mfma_f32_16x16x32_bf16 v[112:115], v[202:205], v[170:173], v[112:115]
	v_mfma_f32_16x16x32_bf16 v[104:107], v[210:213], v[170:173], v[104:107]
	v_mfma_f32_16x16x32_bf16 v[92:95], v[202:205], v[178:181], v[92:95]
	v_mfma_f32_16x16x32_bf16 v[88:91], v[210:213], v[178:181], v[88:91]
	v_mfma_f32_16x16x32_bf16 v[76:79], v[202:205], v[186:189], v[76:79]
	v_mfma_f32_16x16x32_bf16 v[72:75], v[210:213], v[186:189], v[72:75]
	v_mfma_f32_16x16x32_bf16 v[68:71], v[202:205], v[194:197], v[68:71]
	v_mfma_f32_16x16x32_bf16 v[64:67], v[210:213], v[194:197], v[64:67]
	s_setprio 0
	s_mov_b32 m0, s60
	v_lshl_add_u64 v[214:215], v[218:219], 0, s[6:7]
	s_barrier
	ds_read_b128 v[166:169], v147 offset:49152
	ds_read_b128 v[170:173], v147 offset:50176
	ds_read_b128 v[174:177], v147 offset:51200
	ds_read_b128 v[178:181], v147 offset:52224
	ds_read_b128 v[182:185], v147 offset:53248
	ds_read_b128 v[186:189], v147 offset:54272
	ds_read_b128 v[190:193], v147 offset:55296
	ds_read_b128 v[194:197], v147 offset:56320
	global_load_lds_dwordx4 v[214:215], off
	v_lshl_add_u64 v[214:215], v[220:221], 0, s[6:7]
	s_mov_b32 m0, s61
	s_nop 0
	global_load_lds_dwordx4 v[214:215], off
	s_barrier
	s_waitcnt lgkmcnt(0)
	s_setprio 1
	s_waitcnt lgkmcnt(0)
	v_mfma_f32_16x16x32_bf16 v[60:63], v[150:153], v[166:169], v[60:63]
	v_mfma_f32_16x16x32_bf16 v[56:59], v[158:161], v[166:169], v[56:59]
	v_mfma_f32_16x16x32_bf16 v[52:55], v[150:153], v[174:177], v[52:55]
	v_mfma_f32_16x16x32_bf16 v[48:51], v[158:161], v[174:177], v[48:51]
	v_mfma_f32_16x16x32_bf16 v[36:39], v[150:153], v[182:185], v[36:39]
	v_mfma_f32_16x16x32_bf16 v[32:35], v[158:161], v[182:185], v[32:35]
	v_mfma_f32_16x16x32_bf16 v[20:23], v[150:153], v[190:193], v[20:23]
	v_mfma_f32_16x16x32_bf16 v[16:19], v[158:161], v[190:193], v[16:19]
	v_mfma_f32_16x16x32_bf16 v[60:63], v[154:157], v[170:173], v[60:63]
	v_mfma_f32_16x16x32_bf16 v[56:59], v[162:165], v[170:173], v[56:59]
	v_mfma_f32_16x16x32_bf16 v[52:55], v[154:157], v[178:181], v[52:55]
	v_mfma_f32_16x16x32_bf16 v[48:51], v[162:165], v[178:181], v[48:51]
	v_mfma_f32_16x16x32_bf16 v[36:39], v[154:157], v[186:189], v[36:39]
	v_mfma_f32_16x16x32_bf16 v[32:35], v[162:165], v[186:189], v[32:35]
	v_mfma_f32_16x16x32_bf16 v[20:23], v[154:157], v[194:197], v[20:23]
	v_mfma_f32_16x16x32_bf16 v[16:19], v[162:165], v[194:197], v[16:19]
	s_setprio 0
	s_barrier
	s_add_u32 s36, s36, 0x80080
	s_addc_u32 s37, s37, 0
	s_add_i32 s54, s54, s33
	v_lshl_add_u64 v[150:151], s[36:37], 0, v[130:131]
	s_mov_b32 m0, s54
	s_nop 0
	global_load_lds_dwordx4 v[150:151], off
	v_lshl_add_u64 v[150:151], s[36:37], 0, v[134:135]
	s_add_i32 m0, s54, 0x2000
	s_nop 0
	global_load_lds_dwordx4 v[150:151], off
	s_waitcnt vmcnt(6)
	s_barrier
	s_setprio 1
	v_mfma_f32_16x16x32_bf16 v[44:47], v[198:201], v[166:169], v[44:47]
	v_mfma_f32_16x16x32_bf16 v[40:43], v[206:209], v[166:169], v[40:43]
	v_mfma_f32_16x16x32_bf16 v[28:31], v[198:201], v[174:177], v[28:31]
	v_mfma_f32_16x16x32_bf16 v[24:27], v[206:209], v[174:177], v[24:27]
	v_mfma_f32_16x16x32_bf16 v[12:15], v[198:201], v[182:185], v[12:15]
	v_mfma_f32_16x16x32_bf16 v[8:11], v[206:209], v[182:185], v[8:11]
	v_mfma_f32_16x16x32_bf16 v[4:7], v[198:201], v[190:193], v[4:7]
	v_mfma_f32_16x16x32_bf16 v[0:3], v[206:209], v[190:193], v[0:3]
	v_mfma_f32_16x16x32_bf16 v[44:47], v[202:205], v[170:173], v[44:47]
	v_mfma_f32_16x16x32_bf16 v[40:43], v[210:213], v[170:173], v[40:43]
	v_mfma_f32_16x16x32_bf16 v[28:31], v[202:205], v[178:181], v[28:31]
	v_mfma_f32_16x16x32_bf16 v[24:27], v[210:213], v[178:181], v[24:27]
	v_mfma_f32_16x16x32_bf16 v[12:15], v[202:205], v[186:189], v[12:15]
	v_mfma_f32_16x16x32_bf16 v[8:11], v[210:213], v[186:189], v[8:11]
	v_mfma_f32_16x16x32_bf16 v[4:7], v[202:205], v[194:197], v[4:7]
	v_mfma_f32_16x16x32_bf16 v[0:3], v[210:213], v[194:197], v[0:3]
	s_setprio 0
	s_add_i32 s73, s73, 2
	s_add_u32 s18, s18, 0x100
	s_addc_u32 s19, s19, 0
	s_add_u32 s29, s29, 0x100
	s_addc_u32 s72, s72, 0
	s_cmp_gt_u32 s73, 29
	s_barrier
	s_cbranch_scc0 .LBB0_243

.LBB0_329:
	s_ashr_i32 s15, s14, 31
	s_xor_b64 s[16:17], s[28:29], -1
	s_lshl_b64 s[18:19], s[14:15], 20
	s_add_u32 s18, s58, s18
	s_addc_u32 s19, s59, s19
	s_and_b64 s[30:31], s[28:29], exec
	s_cselect_b32 s1, s19, s37
	s_cselect_b32 s15, s18, s36
	s_ashr_i32 s13, s12, 31
	s_lshl_b64 s[30:31], s[12:13], 20
	s_add_u32 s30, s22, s30
	s_addc_u32 s31, s23, s31
	s_and_b64 s[28:29], s[28:29], exec
	s_cselect_b32 s13, s31, s55
	s_cselect_b32 s28, s30, s54
	s_add_u32 s36, s36, 0x80080
	s_addc_u32 s37, s37, 0
	s_add_u32 s29, s54, 0x100
	s_addc_u32 s35, s55, 0
	s_mov_b32 s78, -2
	ds_read_b128 v[146:149], v152
	ds_read_b128 v[156:159], v152 offset:1024
	ds_read_b128 v[160:163], v152 offset:2048
	ds_read_b128 v[164:167], v152 offset:3072
	s_add_u32 s54, s36, 0xfff80080
	s_addc_u32 s55, s37, -1
	s_cmp_eq_u32 s78, 28
	s_cselect_b32 s57, s1, s55
	s_cselect_b32 s56, s15, s54
	s_cselect_b32 s55, s13, s35
	s_cselect_b32 s54, s28, s29
	v_lshl_add_u64 v[200:201], s[36:37], 0, v[138:139]
	s_add_i32 m0, s61, 0xc000
	ds_read_b128 v[168:171], v153
	ds_read_b128 v[172:175], v153 offset:1024
	ds_read_b128 v[176:179], v153 offset:2048
	ds_read_b128 v[180:183], v153 offset:3072
	ds_read_b128 v[184:187], v153 offset:4096
	ds_read_b128 v[188:191], v153 offset:5120
	ds_read_b128 v[192:195], v153 offset:6144
	ds_read_b128 v[196:199], v153 offset:7168
	global_load_lds_dwordx4 v[200:201], off
	v_lshl_add_u64 v[200:201], s[36:37], 0, v[140:141]
	s_add_i32 m0, s61, 0xe000
	s_nop 0
	global_load_lds_dwordx4 v[200:201], off
	s_waitcnt lgkmcnt(8)
	s_barrier
	s_waitcnt lgkmcnt(0)
	s_setprio 1
	s_waitcnt lgkmcnt(0)
	v_mfma_f32_16x16x32_bf16 v[124:127], v[146:149], v[168:171], 0
	v_mfma_f32_16x16x32_bf16 v[120:123], v[160:163], v[168:171], 0
	v_mfma_f32_16x16x32_bf16 v[108:111], v[146:149], v[176:179], 0
	v_mfma_f32_16x16x32_bf16 v[104:107], v[160:163], v[176:179], 0
	v_mfma_f32_16x16x32_bf16 v[92:95], v[146:149], v[184:187], 0
	v_mfma_f32_16x16x32_bf16 v[88:91], v[160:163], v[184:187], 0
	v_mfma_f32_16x16x32_bf16 v[76:79], v[146:149], v[192:195], 0
	v_mfma_f32_16x16x32_bf16 v[72:75], v[160:163], v[192:195], 0
	v_mfma_f32_16x16x32_bf16 v[124:127], v[156:159], v[172:175], v[124:127]
	v_mfma_f32_16x16x32_bf16 v[120:123], v[164:167], v[172:175], v[120:123]
	v_mfma_f32_16x16x32_bf16 v[108:111], v[156:159], v[180:183], v[108:111]
	v_mfma_f32_16x16x32_bf16 v[104:107], v[164:167], v[180:183], v[104:107]
	v_mfma_f32_16x16x32_bf16 v[92:95], v[156:159], v[188:191], v[92:95]
	v_mfma_f32_16x16x32_bf16 v[88:91], v[164:167], v[188:191], v[88:91]
	v_mfma_f32_16x16x32_bf16 v[76:79], v[156:159], v[196:199], v[76:79]
	v_mfma_f32_16x16x32_bf16 v[72:75], v[164:167], v[196:199], v[72:75]
	s_setprio 0
	s_barrier
	s_add_i32 s79, s75, s60
	v_lshl_add_u64 v[216:217], s[54:55], 0, v[130:131]
	s_mov_b32 m0, s79
	ds_read_b128 v[200:203], v154
	ds_read_b128 v[204:207], v154 offset:1024
	ds_read_b128 v[208:211], v154 offset:2048
	ds_read_b128 v[212:215], v154 offset:3072
	global_load_lds_dwordx4 v[216:217], off
	v_lshl_add_u64 v[218:219], s[54:55], 0, v[134:135]
	s_add_i32 m0, s79, 0x2000
	s_nop 0
	global_load_lds_dwordx4 v[218:219], off
	s_barrier
	s_waitcnt lgkmcnt(0)
	s_setprio 1
	s_waitcnt lgkmcnt(0)
	v_mfma_f32_16x16x32_bf16 v[116:119], v[200:203], v[168:171], 0
	v_mfma_f32_16x16x32_bf16 v[112:115], v[208:211], v[168:171], 0
	v_mfma_f32_16x16x32_bf16 v[100:103], v[200:203], v[176:179], 0
	v_mfma_f32_16x16x32_bf16 v[96:99], v[208:211], v[176:179], 0
	v_mfma_f32_16x16x32_bf16 v[84:87], v[200:203], v[184:187], 0
	v_mfma_f32_16x16x32_bf16 v[80:83], v[208:211], v[184:187], 0
	v_mfma_f32_16x16x32_bf16 v[68:71], v[200:203], v[192:195], 0
	v_mfma_f32_16x16x32_bf16 v[64:67], v[208:211], v[192:195], 0
	v_mfma_f32_16x16x32_bf16 v[116:119], v[204:207], v[172:175], v[116:119]
	v_mfma_f32_16x16x32_bf16 v[112:115], v[212:215], v[172:175], v[112:115]
	v_mfma_f32_16x16x32_bf16 v[100:103], v[204:207], v[180:183], v[100:103]
	v_mfma_f32_16x16x32_bf16 v[96:99], v[212:215], v[180:183], v[96:99]
	v_mfma_f32_16x16x32_bf16 v[84:87], v[204:207], v[188:191], v[84:87]
	v_mfma_f32_16x16x32_bf16 v[80:83], v[212:215], v[188:191], v[80:83]
	v_mfma_f32_16x16x32_bf16 v[68:71], v[204:207], v[196:199], v[68:71]
	v_mfma_f32_16x16x32_bf16 v[64:67], v[212:215], v[196:199], v[64:67]
	s_setprio 0
	s_mov_b32 m0, s61
	v_lshl_add_u64 v[220:221], s[56:57], 0, v[128:129]
	s_barrier
	ds_read_b128 v[168:171], v153 offset:16384
	ds_read_b128 v[172:175], v153 offset:17408
	ds_read_b128 v[176:179], v153 offset:18432
	ds_read_b128 v[180:183], v153 offset:19456
	ds_read_b128 v[184:187], v153 offset:20480
	ds_read_b128 v[188:191], v153 offset:21504
	ds_read_b128 v[192:195], v153 offset:22528
	ds_read_b128 v[196:199], v153 offset:23552
	global_load_lds_dwordx4 v[220:221], off
	v_lshl_add_u64 v[222:223], s[56:57], 0, v[132:133]
	s_mov_b32 m0, s62
	s_nop 0
	global_load_lds_dwordx4 v[222:223], off
	s_barrier
	s_waitcnt lgkmcnt(0)
	s_setprio 1
	s_waitcnt lgkmcnt(0)
	v_mfma_f32_16x16x32_bf16 v[60:63], v[146:149], v[168:171], 0
	v_mfma_f32_16x16x32_bf16 v[56:59], v[160:163], v[168:171], 0
	v_mfma_f32_16x16x32_bf16 v[44:47], v[146:149], v[176:179], 0
	v_mfma_f32_16x16x32_bf16 v[40:43], v[160:163], v[176:179], 0
	v_mfma_f32_16x16x32_bf16 v[28:31], v[146:149], v[184:187], 0
	v_mfma_f32_16x16x32_bf16 v[24:27], v[160:163], v[184:187], 0
	v_mfma_f32_16x16x32_bf16 v[12:15], v[146:149], v[192:195], 0
	v_mfma_f32_16x16x32_bf16 v[8:11], v[160:163], v[192:195], 0
	v_mfma_f32_16x16x32_bf16 v[60:63], v[156:159], v[172:175], v[60:63]
	v_mfma_f32_16x16x32_bf16 v[56:59], v[164:167], v[172:175], v[56:59]
	v_mfma_f32_16x16x32_bf16 v[44:47], v[156:159], v[180:183], v[44:47]
	v_mfma_f32_16x16x32_bf16 v[40:43], v[164:167], v[180:183], v[40:43]
	v_mfma_f32_16x16x32_bf16 v[28:31], v[156:159], v[188:191], v[28:31]
	v_mfma_f32_16x16x32_bf16 v[24:27], v[164:167], v[188:191], v[24:27]
	v_mfma_f32_16x16x32_bf16 v[12:15], v[156:159], v[196:199], v[12:15]
	v_mfma_f32_16x16x32_bf16 v[8:11], v[164:167], v[196:199], v[8:11]
	s_setprio 0
	s_barrier
	s_add_u32 s80, s54, 0x80000
	s_addc_u32 s81, s55, 0
	s_add_i32 s79, s76, s60
	v_lshl_add_u64 v[146:147], s[80:81], 0, v[130:131]
	s_mov_b32 m0, s79
	s_nop 0
	global_load_lds_dwordx4 v[146:147], off
	v_lshl_add_u64 v[146:147], s[80:81], 0, v[134:135]
	s_add_i32 m0, s79, 0x2000
	s_nop 0
	global_load_lds_dwordx4 v[146:147], off
	s_waitcnt vmcnt(6)
	s_barrier
	s_setprio 1
	v_mfma_f32_16x16x32_bf16 v[52:55], v[200:203], v[168:171], 0
	v_mfma_f32_16x16x32_bf16 v[48:51], v[208:211], v[168:171], 0
	v_mfma_f32_16x16x32_bf16 v[36:39], v[200:203], v[176:179], 0
	v_mfma_f32_16x16x32_bf16 v[32:35], v[208:211], v[176:179], 0
	v_mfma_f32_16x16x32_bf16 v[20:23], v[200:203], v[184:187], 0
	v_mfma_f32_16x16x32_bf16 v[16:19], v[208:211], v[184:187], 0
	v_mfma_f32_16x16x32_bf16 v[4:7], v[200:203], v[192:195], 0
	v_mfma_f32_16x16x32_bf16 v[0:3], v[208:211], v[192:195], 0
	v_mfma_f32_16x16x32_bf16 v[52:55], v[204:207], v[172:175], v[52:55]
	v_mfma_f32_16x16x32_bf16 v[48:51], v[212:215], v[172:175], v[48:51]
	v_mfma_f32_16x16x32_bf16 v[36:39], v[204:207], v[180:183], v[36:39]
	v_mfma_f32_16x16x32_bf16 v[32:35], v[212:215], v[180:183], v[32:35]
	v_mfma_f32_16x16x32_bf16 v[20:23], v[204:207], v[188:191], v[20:23]
	v_mfma_f32_16x16x32_bf16 v[16:19], v[212:215], v[188:191], v[16:19]
	v_mfma_f32_16x16x32_bf16 v[4:7], v[204:207], v[196:199], v[4:7]
	v_mfma_f32_16x16x32_bf16 v[0:3], v[212:215], v[196:199], v[0:3]
	s_setprio 0
	s_add_i32 s79, 0, 0x18000
	v_add_u32_e32 v155, s79, v150
	s_barrier
	ds_read_b128 v[146:149], v155
	ds_read_b128 v[156:159], v155 offset:1024
	ds_read_b128 v[160:163], v155 offset:2048
	ds_read_b128 v[164:167], v155 offset:3072
	s_add_u32 s56, s56, 0x80000
	s_addc_u32 s57, s57, 0
	s_mov_b32 m0, s63
	v_lshl_add_u64 v[200:201], s[56:57], 0, v[128:129]
	ds_read_b128 v[168:171], v153 offset:32768
	ds_read_b128 v[172:175], v153 offset:33792
	ds_read_b128 v[176:179], v153 offset:34816
	ds_read_b128 v[180:183], v153 offset:35840
	ds_read_b128 v[184:187], v153 offset:36864
	ds_read_b128 v[188:191], v153 offset:37888
	ds_read_b128 v[192:195], v153 offset:38912
	ds_read_b128 v[196:199], v153 offset:39936
	global_load_lds_dwordx4 v[200:201], off
	v_lshl_add_u64 v[200:201], s[56:57], 0, v[132:133]
	s_mov_b32 m0, s64
	s_nop 0
	global_load_lds_dwordx4 v[200:201], off
	s_waitcnt lgkmcnt(8)
	s_barrier
	s_waitcnt lgkmcnt(0)
	s_setprio 1
	s_waitcnt lgkmcnt(0)
	v_mfma_f32_16x16x32_bf16 v[124:127], v[146:149], v[168:171], v[124:127]
	v_mfma_f32_16x16x32_bf16 v[120:123], v[160:163], v[168:171], v[120:123]
	v_mfma_f32_16x16x32_bf16 v[108:111], v[146:149], v[176:179], v[108:111]
	v_mfma_f32_16x16x32_bf16 v[104:107], v[160:163], v[176:179], v[104:107]
	v_mfma_f32_16x16x32_bf16 v[92:95], v[146:149], v[184:187], v[92:95]
	v_mfma_f32_16x16x32_bf16 v[88:91], v[160:163], v[184:187], v[88:91]
	v_mfma_f32_16x16x32_bf16 v[76:79], v[146:149], v[192:195], v[76:79]
	v_mfma_f32_16x16x32_bf16 v[72:75], v[160:163], v[192:195], v[72:75]
	v_mfma_f32_16x16x32_bf16 v[124:127], v[156:159], v[172:175], v[124:127]
	v_mfma_f32_16x16x32_bf16 v[120:123], v[164:167], v[172:175], v[120:123]
	v_mfma_f32_16x16x32_bf16 v[108:111], v[156:159], v[180:183], v[108:111]
	v_mfma_f32_16x16x32_bf16 v[104:107], v[164:167], v[180:183], v[104:107]
	v_mfma_f32_16x16x32_bf16 v[92:95], v[156:159], v[188:191], v[92:95]
	v_mfma_f32_16x16x32_bf16 v[88:91], v[164:167], v[188:191], v[88:91]
	v_mfma_f32_16x16x32_bf16 v[76:79], v[156:159], v[196:199], v[76:79]
	v_mfma_f32_16x16x32_bf16 v[72:75], v[164:167], v[196:199], v[72:75]
	s_setprio 0
	s_barrier
	s_add_i32 s56, 0, 0x1c000
	s_add_i32 s57, s79, s60
	v_add_u32_e32 v155, s56, v150
	v_lshl_add_u64 v[216:217], v[216:217], 0, s[10:11]
	s_mov_b32 m0, s57
	ds_read_b128 v[200:203], v155
	ds_read_b128 v[204:207], v155 offset:1024
	ds_read_b128 v[208:211], v155 offset:2048
	ds_read_b128 v[212:215], v155 offset:3072
	global_load_lds_dwordx4 v[216:217], off
	v_lshl_add_u64 v[216:217], v[218:219], 0, s[10:11]
	s_add_i32 m0, s57, 0x2000
	s_nop 0
	global_load_lds_dwordx4 v[216:217], off
	s_barrier
	s_waitcnt lgkmcnt(0)
	s_setprio 1
	s_waitcnt lgkmcnt(0)
	v_mfma_f32_16x16x32_bf16 v[116:119], v[200:203], v[168:171], v[116:119]
	v_mfma_f32_16x16x32_bf16 v[112:115], v[208:211], v[168:171], v[112:115]
	v_mfma_f32_16x16x32_bf16 v[100:103], v[200:203], v[176:179], v[100:103]
	v_mfma_f32_16x16x32_bf16 v[96:99], v[208:211], v[176:179], v[96:99]
	v_mfma_f32_16x16x32_bf16 v[84:87], v[200:203], v[184:187], v[84:87]
	v_mfma_f32_16x16x32_bf16 v[80:83], v[208:211], v[184:187], v[80:83]
	v_mfma_f32_16x16x32_bf16 v[68:71], v[200:203], v[192:195], v[68:71]
	v_mfma_f32_16x16x32_bf16 v[64:67], v[208:211], v[192:195], v[64:67]
	v_mfma_f32_16x16x32_bf16 v[116:119], v[204:207], v[172:175], v[116:119]
	v_mfma_f32_16x16x32_bf16 v[112:115], v[212:215], v[172:175], v[112:115]
	v_mfma_f32_16x16x32_bf16 v[100:103], v[204:207], v[180:183], v[100:103]
	v_mfma_f32_16x16x32_bf16 v[96:99], v[212:215], v[180:183], v[96:99]
	v_mfma_f32_16x16x32_bf16 v[84:87], v[204:207], v[188:191], v[84:87]
	v_mfma_f32_16x16x32_bf16 v[80:83], v[212:215], v[188:191], v[80:83]
	v_mfma_f32_16x16x32_bf16 v[68:71], v[204:207], v[196:199], v[68:71]
	v_mfma_f32_16x16x32_bf16 v[64:67], v[212:215], v[196:199], v[64:67]
	s_setprio 0
	s_mov_b32 m0, s66
	v_lshl_add_u64 v[216:217], v[220:221], 0, s[10:11]
	s_barrier
	ds_read_b128 v[168:171], v153 offset:49152
	ds_read_b128 v[172:175], v153 offset:50176
	ds_read_b128 v[176:179], v153 offset:51200
	ds_read_b128 v[180:183], v153 offset:52224
	ds_read_b128 v[184:187], v153 offset:53248
	ds_read_b128 v[188:191], v153 offset:54272
	ds_read_b128 v[192:195], v153 offset:55296
	ds_read_b128 v[196:199], v153 offset:56320
	global_load_lds_dwordx4 v[216:217], off
	v_lshl_add_u64 v[216:217], v[222:223], 0, s[10:11]
	s_mov_b32 m0, s67
	s_nop 0
	global_load_lds_dwordx4 v[216:217], off
	s_barrier
	s_waitcnt lgkmcnt(0)
	s_setprio 1
	s_waitcnt lgkmcnt(0)
	v_mfma_f32_16x16x32_bf16 v[60:63], v[146:149], v[168:171], v[60:63]
	v_mfma_f32_16x16x32_bf16 v[56:59], v[160:163], v[168:171], v[56:59]
	v_mfma_f32_16x16x32_bf16 v[44:47], v[146:149], v[176:179], v[44:47]
	v_mfma_f32_16x16x32_bf16 v[40:43], v[160:163], v[176:179], v[40:43]
	v_mfma_f32_16x16x32_bf16 v[28:31], v[146:149], v[184:187], v[28:31]
	v_mfma_f32_16x16x32_bf16 v[24:27], v[160:163], v[184:187], v[24:27]
	v_mfma_f32_16x16x32_bf16 v[12:15], v[146:149], v[192:195], v[12:15]
	v_mfma_f32_16x16x32_bf16 v[8:11], v[160:163], v[192:195], v[8:11]
	v_mfma_f32_16x16x32_bf16 v[60:63], v[156:159], v[172:175], v[60:63]
	v_mfma_f32_16x16x32_bf16 v[56:59], v[164:167], v[172:175], v[56:59]
	v_mfma_f32_16x16x32_bf16 v[44:47], v[156:159], v[180:183], v[44:47]
	v_mfma_f32_16x16x32_bf16 v[40:43], v[164:167], v[180:183], v[40:43]
	v_mfma_f32_16x16x32_bf16 v[28:31], v[156:159], v[188:191], v[28:31]
	v_mfma_f32_16x16x32_bf16 v[24:27], v[164:167], v[188:191], v[24:27]
	v_mfma_f32_16x16x32_bf16 v[12:15], v[156:159], v[196:199], v[12:15]
	v_mfma_f32_16x16x32_bf16 v[8:11], v[164:167], v[196:199], v[8:11]
	s_setprio 0
	s_barrier
	s_add_u32 s54, s54, 0x80080
	s_addc_u32 s55, s55, 0
	s_add_i32 s56, s56, s60
	v_lshl_add_u64 v[146:147], s[54:55], 0, v[130:131]
	s_mov_b32 m0, s56
	s_nop 0
	global_load_lds_dwordx4 v[146:147], off
	v_lshl_add_u64 v[146:147], s[54:55], 0, v[134:135]
	s_add_i32 m0, s56, 0x2000
	s_nop 0
	global_load_lds_dwordx4 v[146:147], off
	s_waitcnt vmcnt(6)
	s_barrier
	s_setprio 1
	v_mfma_f32_16x16x32_bf16 v[52:55], v[200:203], v[168:171], v[52:55]
	v_mfma_f32_16x16x32_bf16 v[48:51], v[208:211], v[168:171], v[48:51]
	v_mfma_f32_16x16x32_bf16 v[36:39], v[200:203], v[176:179], v[36:39]
	v_mfma_f32_16x16x32_bf16 v[32:35], v[208:211], v[176:179], v[32:35]
	v_mfma_f32_16x16x32_bf16 v[20:23], v[200:203], v[184:187], v[20:23]
	v_mfma_f32_16x16x32_bf16 v[16:19], v[208:211], v[184:187], v[16:19]
	v_mfma_f32_16x16x32_bf16 v[4:7], v[200:203], v[192:195], v[4:7]
	v_mfma_f32_16x16x32_bf16 v[0:3], v[208:211], v[192:195], v[0:3]
	v_mfma_f32_16x16x32_bf16 v[52:55], v[204:207], v[172:175], v[52:55]
	v_mfma_f32_16x16x32_bf16 v[48:51], v[212:215], v[172:175], v[48:51]
	v_mfma_f32_16x16x32_bf16 v[36:39], v[204:207], v[180:183], v[36:39]
	v_mfma_f32_16x16x32_bf16 v[32:35], v[212:215], v[180:183], v[32:35]
	v_mfma_f32_16x16x32_bf16 v[20:23], v[204:207], v[188:191], v[20:23]
	v_mfma_f32_16x16x32_bf16 v[16:19], v[212:215], v[188:191], v[16:19]
	v_mfma_f32_16x16x32_bf16 v[4:7], v[204:207], v[196:199], v[4:7]
	v_mfma_f32_16x16x32_bf16 v[0:3], v[212:215], v[196:199], v[0:3]
	s_setprio 0
	s_add_i32 s78, s78, 2
	s_add_u32 s36, s36, 0x100
	s_addc_u32 s37, s37, 0
	s_add_u32 s29, s29, 0x100
	s_addc_u32 s35, s35, 0
	s_cmp_gt_u32 s78, 29
	s_barrier
	s_cbranch_scc0 .LBB0_330

.LBB0_931:
	s_ashr_i32 s15, s14, 31
	s_xor_b64 s[16:17], s[28:29], -1
	s_lshl_b64 s[18:19], s[14:15], 19
	s_add_u32 s18, s42, s18
	s_addc_u32 s19, s43, s19
	s_and_b64 s[30:31], s[28:29], exec
	s_cselect_b32 s15, s19, s37
	s_cselect_b32 s63, s18, s36
	s_ashr_i32 s13, s12, 31
	s_lshl_b64 s[30:31], s[12:13], 19
	s_add_u32 s30, s44, s30
	s_addc_u32 s31, s45, s31
	s_and_b64 s[28:29], s[28:29], exec
	s_cselect_b32 s13, s31, s39
	s_cselect_b32 s28, s30, s38
	s_add_u32 s36, s36, 0x40080
	s_addc_u32 s37, s37, 0
	s_add_u32 s29, s38, 0x100
	s_addc_u32 s64, s39, 0
	s_mov_b32 s65, -2
	ds_read_b128 v[128:131], v169
	ds_read_b128 v[132:135], v169 offset:1024
	ds_read_b128 v[136:139], v169 offset:2048
	ds_read_b128 v[140:143], v169 offset:3072
	s_add_u32 s38, s36, 0xfffc0080
	s_addc_u32 s39, s37, -1
	s_cmp_eq_u32 s65, 12
	s_cselect_b32 s41, s15, s39
	s_cselect_b32 s40, s63, s38
	s_cselect_b32 s39, s13, s64
	s_cselect_b32 s38, s28, s29
	v_lshl_add_u64 v[164:165], s[36:37], 0, v[154:155]
	s_add_i32 m0, s35, 0xc000
	ds_read_b128 v[160:163], v170
	ds_read_b128 v[172:175], v170 offset:1024
	ds_read_b128 v[176:179], v170 offset:2048
	ds_read_b128 v[180:183], v170 offset:3072
	ds_read_b128 v[184:187], v170 offset:4096
	ds_read_b128 v[188:191], v170 offset:5120
	ds_read_b128 v[192:195], v170 offset:6144
	ds_read_b128 v[196:199], v170 offset:7168
	global_load_lds_dwordx4 v[164:165], off
	v_lshl_add_u64 v[164:165], s[36:37], 0, v[156:157]
	s_add_i32 m0, s35, 0xe000
	s_nop 0
	global_load_lds_dwordx4 v[164:165], off
	s_waitcnt lgkmcnt(8)
	s_barrier
	s_waitcnt lgkmcnt(0)
	s_setprio 1
	s_waitcnt lgkmcnt(0)
	v_mfma_f32_16x16x32_bf16 v[124:127], v[128:131], v[160:163], 0
	v_mfma_f32_16x16x32_bf16 v[120:123], v[136:139], v[160:163], 0
	v_mfma_f32_16x16x32_bf16 v[116:119], v[128:131], v[176:179], 0
	v_mfma_f32_16x16x32_bf16 v[100:103], v[136:139], v[176:179], 0
	v_mfma_f32_16x16x32_bf16 v[92:95], v[128:131], v[184:187], 0
	v_mfma_f32_16x16x32_bf16 v[84:87], v[136:139], v[184:187], 0
	v_mfma_f32_16x16x32_bf16 v[76:79], v[128:131], v[192:195], 0
	v_mfma_f32_16x16x32_bf16 v[68:71], v[136:139], v[192:195], 0
	v_mfma_f32_16x16x32_bf16 v[124:127], v[132:135], v[172:175], v[124:127]
	v_mfma_f32_16x16x32_bf16 v[120:123], v[140:143], v[172:175], v[120:123]
	v_mfma_f32_16x16x32_bf16 v[116:119], v[132:135], v[180:183], v[116:119]
	v_mfma_f32_16x16x32_bf16 v[100:103], v[140:143], v[180:183], v[100:103]
	v_mfma_f32_16x16x32_bf16 v[92:95], v[132:135], v[188:191], v[92:95]
	v_mfma_f32_16x16x32_bf16 v[84:87], v[140:143], v[188:191], v[84:87]
	v_mfma_f32_16x16x32_bf16 v[76:79], v[132:135], v[196:199], v[76:79]
	v_mfma_f32_16x16x32_bf16 v[68:71], v[140:143], v[196:199], v[68:71]
	s_setprio 0
	s_barrier
	s_add_i32 s66, s57, s46
	v_lshl_add_u64 v[164:165], s[38:39], 0, v[148:149]
	s_mov_b32 m0, s66
	ds_read_b128 v[200:203], v171
	ds_read_b128 v[204:207], v171 offset:1024
	ds_read_b128 v[208:211], v171 offset:2048
	ds_read_b128 v[212:215], v171 offset:3072
	global_load_lds_dwordx4 v[164:165], off
	v_lshl_add_u64 v[216:217], s[38:39], 0, v[152:153]
	s_add_i32 m0, s66, 0x2000
	s_nop 0
	global_load_lds_dwordx4 v[216:217], off
	s_barrier
	s_waitcnt lgkmcnt(0)
	s_setprio 1
	s_waitcnt lgkmcnt(0)
	v_mfma_f32_16x16x32_bf16 v[112:115], v[200:203], v[160:163], 0
	v_mfma_f32_16x16x32_bf16 v[108:111], v[208:211], v[160:163], 0
	v_mfma_f32_16x16x32_bf16 v[104:107], v[200:203], v[176:179], 0
	v_mfma_f32_16x16x32_bf16 v[96:99], v[208:211], v[176:179], 0
	v_mfma_f32_16x16x32_bf16 v[88:91], v[200:203], v[184:187], 0
	v_mfma_f32_16x16x32_bf16 v[80:83], v[208:211], v[184:187], 0
	v_mfma_f32_16x16x32_bf16 v[72:75], v[200:203], v[192:195], 0
	v_mfma_f32_16x16x32_bf16 v[64:67], v[208:211], v[192:195], 0
	v_mfma_f32_16x16x32_bf16 v[112:115], v[204:207], v[172:175], v[112:115]
	v_mfma_f32_16x16x32_bf16 v[108:111], v[212:215], v[172:175], v[108:111]
	v_mfma_f32_16x16x32_bf16 v[104:107], v[204:207], v[180:183], v[104:107]
	v_mfma_f32_16x16x32_bf16 v[96:99], v[212:215], v[180:183], v[96:99]
	v_mfma_f32_16x16x32_bf16 v[88:91], v[204:207], v[188:191], v[88:91]
	v_mfma_f32_16x16x32_bf16 v[80:83], v[212:215], v[188:191], v[80:83]
	v_mfma_f32_16x16x32_bf16 v[72:75], v[204:207], v[196:199], v[72:75]
	v_mfma_f32_16x16x32_bf16 v[64:67], v[212:215], v[196:199], v[64:67]
	s_setprio 0
	s_mov_b32 m0, s35
	v_lshl_add_u64 v[218:219], s[40:41], 0, v[146:147]
	s_barrier
	ds_read_b128 v[160:163], v170 offset:16384
	ds_read_b128 v[172:175], v170 offset:17408
	ds_read_b128 v[176:179], v170 offset:18432
	ds_read_b128 v[180:183], v170 offset:19456
	ds_read_b128 v[184:187], v170 offset:20480
	ds_read_b128 v[188:191], v170 offset:21504
	ds_read_b128 v[192:195], v170 offset:22528
	ds_read_b128 v[196:199], v170 offset:23552
	global_load_lds_dwordx4 v[218:219], off
	v_lshl_add_u64 v[220:221], s[40:41], 0, v[150:151]
	s_mov_b32 m0, s47
	s_nop 0
	global_load_lds_dwordx4 v[220:221], off
	s_barrier
	s_waitcnt lgkmcnt(0)
	s_setprio 1
	s_waitcnt lgkmcnt(0)
	v_mfma_f32_16x16x32_bf16 v[60:63], v[128:131], v[160:163], 0
	v_mfma_f32_16x16x32_bf16 v[52:55], v[136:139], v[160:163], 0
	v_mfma_f32_16x16x32_bf16 v[44:47], v[128:131], v[176:179], 0
	v_mfma_f32_16x16x32_bf16 v[36:39], v[136:139], v[176:179], 0
	v_mfma_f32_16x16x32_bf16 v[28:31], v[128:131], v[184:187], 0
	v_mfma_f32_16x16x32_bf16 v[20:23], v[136:139], v[184:187], 0
	v_mfma_f32_16x16x32_bf16 v[12:15], v[128:131], v[192:195], 0
	v_mfma_f32_16x16x32_bf16 v[4:7], v[136:139], v[192:195], 0
	v_mfma_f32_16x16x32_bf16 v[60:63], v[132:135], v[172:175], v[60:63]
	v_mfma_f32_16x16x32_bf16 v[52:55], v[140:143], v[172:175], v[52:55]
	v_mfma_f32_16x16x32_bf16 v[44:47], v[132:135], v[180:183], v[44:47]
	v_mfma_f32_16x16x32_bf16 v[36:39], v[140:143], v[180:183], v[36:39]
	v_mfma_f32_16x16x32_bf16 v[28:31], v[132:135], v[188:191], v[28:31]
	v_mfma_f32_16x16x32_bf16 v[20:23], v[140:143], v[188:191], v[20:23]
	v_mfma_f32_16x16x32_bf16 v[12:15], v[132:135], v[196:199], v[12:15]
	v_mfma_f32_16x16x32_bf16 v[4:7], v[140:143], v[196:199], v[4:7]
	s_setprio 0
	s_barrier
	s_add_u32 s66, s38, 0x40000
	s_addc_u32 s67, s39, 0
	s_add_i32 s68, s58, s46
	v_lshl_add_u64 v[128:129], s[66:67], 0, v[148:149]
	s_mov_b32 m0, s68
	s_nop 0
	global_load_lds_dwordx4 v[128:129], off
	v_lshl_add_u64 v[128:129], s[66:67], 0, v[152:153]
	s_add_i32 m0, s68, 0x2000
	s_nop 0
	global_load_lds_dwordx4 v[128:129], off
	s_waitcnt vmcnt(6)
	s_barrier
	s_setprio 1
	v_mfma_f32_16x16x32_bf16 v[56:59], v[200:203], v[160:163], 0
	v_mfma_f32_16x16x32_bf16 v[48:51], v[208:211], v[160:163], 0
	v_mfma_f32_16x16x32_bf16 v[40:43], v[200:203], v[176:179], 0
	v_mfma_f32_16x16x32_bf16 v[32:35], v[208:211], v[176:179], 0
	v_mfma_f32_16x16x32_bf16 v[24:27], v[200:203], v[184:187], 0
	v_mfma_f32_16x16x32_bf16 v[16:19], v[208:211], v[184:187], 0
	v_mfma_f32_16x16x32_bf16 v[8:11], v[200:203], v[192:195], 0
	v_mfma_f32_16x16x32_bf16 v[0:3], v[208:211], v[192:195], 0
	v_mfma_f32_16x16x32_bf16 v[56:59], v[204:207], v[172:175], v[56:59]
	v_mfma_f32_16x16x32_bf16 v[48:51], v[212:215], v[172:175], v[48:51]
	v_mfma_f32_16x16x32_bf16 v[40:43], v[204:207], v[180:183], v[40:43]
	v_mfma_f32_16x16x32_bf16 v[32:35], v[212:215], v[180:183], v[32:35]
	v_mfma_f32_16x16x32_bf16 v[24:27], v[204:207], v[188:191], v[24:27]
	v_mfma_f32_16x16x32_bf16 v[16:19], v[212:215], v[188:191], v[16:19]
	v_mfma_f32_16x16x32_bf16 v[8:11], v[204:207], v[196:199], v[8:11]
	v_mfma_f32_16x16x32_bf16 v[0:3], v[212:215], v[196:199], v[0:3]
	s_setprio 0
	s_add_i32 s66, 0, 0x18000
	v_add_u32_e32 v140, s66, v167
	s_barrier
	ds_read_b128 v[128:131], v140
	ds_read_b128 v[132:135], v140 offset:1024
	ds_read_b128 v[136:139], v140 offset:2048
	ds_read_b128 v[140:143], v140 offset:3072
	s_add_u32 s40, s40, 0x40000
	s_addc_u32 s41, s41, 0
	s_mov_b32 m0, s48
	v_lshl_add_u64 v[200:201], s[40:41], 0, v[146:147]
	ds_read_b128 v[160:163], v170 offset:32768
	ds_read_b128 v[172:175], v170 offset:33792
	ds_read_b128 v[176:179], v170 offset:34816
	ds_read_b128 v[180:183], v170 offset:35840
	ds_read_b128 v[184:187], v170 offset:36864
	ds_read_b128 v[188:191], v170 offset:37888
	ds_read_b128 v[192:195], v170 offset:38912
	ds_read_b128 v[196:199], v170 offset:39936
	global_load_lds_dwordx4 v[200:201], off
	v_lshl_add_u64 v[200:201], s[40:41], 0, v[150:151]
	s_mov_b32 m0, s49
	s_nop 0
	global_load_lds_dwordx4 v[200:201], off
	s_waitcnt lgkmcnt(8)
	s_barrier
	s_waitcnt lgkmcnt(0)
	s_setprio 1
	s_waitcnt lgkmcnt(0)
	v_mfma_f32_16x16x32_bf16 v[124:127], v[128:131], v[160:163], v[124:127]
	v_mfma_f32_16x16x32_bf16 v[120:123], v[136:139], v[160:163], v[120:123]
	v_mfma_f32_16x16x32_bf16 v[116:119], v[128:131], v[176:179], v[116:119]
	v_mfma_f32_16x16x32_bf16 v[100:103], v[136:139], v[176:179], v[100:103]
	v_mfma_f32_16x16x32_bf16 v[92:95], v[128:131], v[184:187], v[92:95]
	v_mfma_f32_16x16x32_bf16 v[84:87], v[136:139], v[184:187], v[84:87]
	v_mfma_f32_16x16x32_bf16 v[76:79], v[128:131], v[192:195], v[76:79]
	v_mfma_f32_16x16x32_bf16 v[68:71], v[136:139], v[192:195], v[68:71]
	v_mfma_f32_16x16x32_bf16 v[124:127], v[132:135], v[172:175], v[124:127]
	v_mfma_f32_16x16x32_bf16 v[120:123], v[140:143], v[172:175], v[120:123]
	v_mfma_f32_16x16x32_bf16 v[116:119], v[132:135], v[180:183], v[116:119]
	v_mfma_f32_16x16x32_bf16 v[100:103], v[140:143], v[180:183], v[100:103]
	v_mfma_f32_16x16x32_bf16 v[92:95], v[132:135], v[188:191], v[92:95]
	v_mfma_f32_16x16x32_bf16 v[84:87], v[140:143], v[188:191], v[84:87]
	v_mfma_f32_16x16x32_bf16 v[76:79], v[132:135], v[196:199], v[76:79]
	v_mfma_f32_16x16x32_bf16 v[68:71], v[140:143], v[196:199], v[68:71]
	s_setprio 0
	s_barrier
	s_add_i32 s40, 0, 0x1c000
	s_add_i32 s41, s66, s46
	v_add_u32_e32 v212, s40, v167
	v_lshl_add_u64 v[164:165], v[164:165], 0, s[8:9]
	s_mov_b32 m0, s41
	ds_read_b128 v[200:203], v212
	ds_read_b128 v[204:207], v212 offset:1024
	ds_read_b128 v[208:211], v212 offset:2048
	ds_read_b128 v[212:215], v212 offset:3072
	global_load_lds_dwordx4 v[164:165], off
	v_lshl_add_u64 v[164:165], v[216:217], 0, s[8:9]
	s_add_i32 m0, s41, 0x2000
	s_nop 0
	global_load_lds_dwordx4 v[164:165], off
	s_barrier
	s_waitcnt lgkmcnt(0)
	s_setprio 1
	s_waitcnt lgkmcnt(0)
	v_mfma_f32_16x16x32_bf16 v[112:115], v[200:203], v[160:163], v[112:115]
	v_mfma_f32_16x16x32_bf16 v[108:111], v[208:211], v[160:163], v[108:111]
	v_mfma_f32_16x16x32_bf16 v[104:107], v[200:203], v[176:179], v[104:107]
	v_mfma_f32_16x16x32_bf16 v[96:99], v[208:211], v[176:179], v[96:99]
	v_mfma_f32_16x16x32_bf16 v[88:91], v[200:203], v[184:187], v[88:91]
	v_mfma_f32_16x16x32_bf16 v[80:83], v[208:211], v[184:187], v[80:83]
	v_mfma_f32_16x16x32_bf16 v[72:75], v[200:203], v[192:195], v[72:75]
	v_mfma_f32_16x16x32_bf16 v[64:67], v[208:211], v[192:195], v[64:67]
	v_mfma_f32_16x16x32_bf16 v[112:115], v[204:207], v[172:175], v[112:115]
	v_mfma_f32_16x16x32_bf16 v[108:111], v[212:215], v[172:175], v[108:111]
	v_mfma_f32_16x16x32_bf16 v[104:107], v[204:207], v[180:183], v[104:107]
	v_mfma_f32_16x16x32_bf16 v[96:99], v[212:215], v[180:183], v[96:99]
	v_mfma_f32_16x16x32_bf16 v[88:91], v[204:207], v[188:191], v[88:91]
	v_mfma_f32_16x16x32_bf16 v[80:83], v[212:215], v[188:191], v[80:83]
	v_mfma_f32_16x16x32_bf16 v[72:75], v[204:207], v[196:199], v[72:75]
	v_mfma_f32_16x16x32_bf16 v[64:67], v[212:215], v[196:199], v[64:67]
	s_setprio 0
	s_mov_b32 m0, s51
	v_lshl_add_u64 v[164:165], v[218:219], 0, s[8:9]
	s_barrier
	ds_read_b128 v[160:163], v170 offset:49152
	ds_read_b128 v[172:175], v170 offset:50176
	ds_read_b128 v[176:179], v170 offset:51200
	ds_read_b128 v[180:183], v170 offset:52224
	ds_read_b128 v[184:187], v170 offset:53248
	ds_read_b128 v[188:191], v170 offset:54272
	ds_read_b128 v[192:195], v170 offset:55296
	ds_read_b128 v[196:199], v170 offset:56320
	global_load_lds_dwordx4 v[164:165], off
	v_lshl_add_u64 v[164:165], v[220:221], 0, s[8:9]
	s_mov_b32 m0, s54
	s_nop 0
	global_load_lds_dwordx4 v[164:165], off
	s_barrier
	s_waitcnt lgkmcnt(0)
	s_setprio 1
	s_waitcnt lgkmcnt(0)
	v_mfma_f32_16x16x32_bf16 v[60:63], v[128:131], v[160:163], v[60:63]
	v_mfma_f32_16x16x32_bf16 v[52:55], v[136:139], v[160:163], v[52:55]
	v_mfma_f32_16x16x32_bf16 v[44:47], v[128:131], v[176:179], v[44:47]
	v_mfma_f32_16x16x32_bf16 v[36:39], v[136:139], v[176:179], v[36:39]
	v_mfma_f32_16x16x32_bf16 v[28:31], v[128:131], v[184:187], v[28:31]
	v_mfma_f32_16x16x32_bf16 v[20:23], v[136:139], v[184:187], v[20:23]
	v_mfma_f32_16x16x32_bf16 v[12:15], v[128:131], v[192:195], v[12:15]
	v_mfma_f32_16x16x32_bf16 v[4:7], v[136:139], v[192:195], v[4:7]
	v_mfma_f32_16x16x32_bf16 v[60:63], v[132:135], v[172:175], v[60:63]
	v_mfma_f32_16x16x32_bf16 v[52:55], v[140:143], v[172:175], v[52:55]
	v_mfma_f32_16x16x32_bf16 v[44:47], v[132:135], v[180:183], v[44:47]
	v_mfma_f32_16x16x32_bf16 v[36:39], v[140:143], v[180:183], v[36:39]
	v_mfma_f32_16x16x32_bf16 v[28:31], v[132:135], v[188:191], v[28:31]
	v_mfma_f32_16x16x32_bf16 v[20:23], v[140:143], v[188:191], v[20:23]
	v_mfma_f32_16x16x32_bf16 v[12:15], v[132:135], v[196:199], v[12:15]
	v_mfma_f32_16x16x32_bf16 v[4:7], v[140:143], v[196:199], v[4:7]
	s_setprio 0
	s_barrier
	s_add_u32 s38, s38, 0x40080
	s_addc_u32 s39, s39, 0
	s_add_i32 s40, s40, s46
	v_lshl_add_u64 v[128:129], s[38:39], 0, v[148:149]
	s_mov_b32 m0, s40
	s_nop 0
	global_load_lds_dwordx4 v[128:129], off
	v_lshl_add_u64 v[128:129], s[38:39], 0, v[152:153]
	s_add_i32 m0, s40, 0x2000
	s_nop 0
	global_load_lds_dwordx4 v[128:129], off
	s_waitcnt vmcnt(6)
	s_barrier
	s_setprio 1
	v_mfma_f32_16x16x32_bf16 v[56:59], v[200:203], v[160:163], v[56:59]
	v_mfma_f32_16x16x32_bf16 v[48:51], v[208:211], v[160:163], v[48:51]
	v_mfma_f32_16x16x32_bf16 v[40:43], v[200:203], v[176:179], v[40:43]
	v_mfma_f32_16x16x32_bf16 v[32:35], v[208:211], v[176:179], v[32:35]
	v_mfma_f32_16x16x32_bf16 v[24:27], v[200:203], v[184:187], v[24:27]
	v_mfma_f32_16x16x32_bf16 v[16:19], v[208:211], v[184:187], v[16:19]
	v_mfma_f32_16x16x32_bf16 v[8:11], v[200:203], v[192:195], v[8:11]
	v_mfma_f32_16x16x32_bf16 v[0:3], v[208:211], v[192:195], v[0:3]
	v_mfma_f32_16x16x32_bf16 v[56:59], v[204:207], v[172:175], v[56:59]
	v_mfma_f32_16x16x32_bf16 v[48:51], v[212:215], v[172:175], v[48:51]
	v_mfma_f32_16x16x32_bf16 v[40:43], v[204:207], v[180:183], v[40:43]
	v_mfma_f32_16x16x32_bf16 v[32:35], v[212:215], v[180:183], v[32:35]
	v_mfma_f32_16x16x32_bf16 v[24:27], v[204:207], v[188:191], v[24:27]
	v_mfma_f32_16x16x32_bf16 v[16:19], v[212:215], v[188:191], v[16:19]
	v_mfma_f32_16x16x32_bf16 v[8:11], v[204:207], v[196:199], v[8:11]
	v_mfma_f32_16x16x32_bf16 v[0:3], v[212:215], v[196:199], v[0:3]
	s_setprio 0
	s_add_i32 s65, s65, 2
	s_add_u32 s36, s36, 0x100
	s_addc_u32 s37, s37, 0
	s_add_u32 s29, s29, 0x100
	s_addc_u32 s64, s64, 0
	s_cmp_gt_u32 s65, 13
	s_barrier
	s_cbranch_scc0 .LBB0_932

.LBB0_1073:
	s_ashr_i32 s31, s30, 31
	s_xor_b64 s[34:35], s[28:29], -1
	s_lshl_b64 s[36:37], s[30:31], 20
	s_add_u32 s36, s48, s36
	s_addc_u32 s37, s49, s37
	s_and_b64 s[38:39], s[28:29], exec
	s_cselect_b32 s31, s37, s43
	s_cselect_b32 s68, s36, s42
	s_ashr_i32 s19, s18, 31
	s_lshl_b64 s[38:39], s[18:19], 20
	s_add_u32 s38, s50, s38
	s_addc_u32 s39, s51, s39
	s_and_b64 s[28:29], s[28:29], exec
	s_cselect_b32 s19, s39, s45
	s_cselect_b32 s28, s38, s44
	s_add_u32 s42, s42, 0x80080
	s_addc_u32 s43, s43, 0
	s_add_u32 s29, s44, 0x100
	s_addc_u32 s69, s45, 0
	s_mov_b32 s70, -2
	ds_read_b128 v[128:131], v165
	ds_read_b128 v[132:135], v165 offset:1024
	ds_read_b128 v[136:139], v165 offset:2048
	ds_read_b128 v[140:143], v165 offset:3072
	s_add_u32 s44, s42, 0xfff80080
	s_addc_u32 s45, s43, -1
	s_cmp_eq_u32 s70, 28
	s_cselect_b32 s47, s31, s45
	s_cselect_b32 s46, s68, s44
	s_cselect_b32 s45, s19, s69
	s_cselect_b32 s44, s28, s29
	v_lshl_add_u64 v[160:161], s[42:43], 0, v[150:151]
	s_add_i32 m0, s41, 0xc000
	ds_read_b128 v[156:159], v166
	ds_read_b128 v[168:171], v166 offset:1024
	ds_read_b128 v[172:175], v166 offset:2048
	ds_read_b128 v[176:179], v166 offset:3072
	ds_read_b128 v[180:183], v166 offset:4096
	ds_read_b128 v[184:187], v166 offset:5120
	ds_read_b128 v[188:191], v166 offset:6144
	ds_read_b128 v[192:195], v166 offset:7168
	global_load_lds_dwordx4 v[160:161], off
	v_lshl_add_u64 v[160:161], s[42:43], 0, v[152:153]
	s_add_i32 m0, s41, 0xe000
	s_nop 0
	global_load_lds_dwordx4 v[160:161], off
	s_waitcnt lgkmcnt(8)
	s_barrier
	s_waitcnt lgkmcnt(0)
	s_setprio 1
	s_waitcnt lgkmcnt(0)
	v_mfma_f32_16x16x32_bf16 v[124:127], v[128:131], v[156:159], 0
	v_mfma_f32_16x16x32_bf16 v[120:123], v[136:139], v[156:159], 0
	v_mfma_f32_16x16x32_bf16 v[112:115], v[128:131], v[172:175], 0
	v_mfma_f32_16x16x32_bf16 v[104:107], v[136:139], v[172:175], 0
	v_mfma_f32_16x16x32_bf16 v[96:99], v[128:131], v[180:183], 0
	v_mfma_f32_16x16x32_bf16 v[88:91], v[136:139], v[180:183], 0
	v_mfma_f32_16x16x32_bf16 v[80:83], v[128:131], v[188:191], 0
	v_mfma_f32_16x16x32_bf16 v[72:75], v[136:139], v[188:191], 0
	v_mfma_f32_16x16x32_bf16 v[124:127], v[132:135], v[168:171], v[124:127]
	v_mfma_f32_16x16x32_bf16 v[120:123], v[140:143], v[168:171], v[120:123]
	v_mfma_f32_16x16x32_bf16 v[112:115], v[132:135], v[176:179], v[112:115]
	v_mfma_f32_16x16x32_bf16 v[104:107], v[140:143], v[176:179], v[104:107]
	v_mfma_f32_16x16x32_bf16 v[96:99], v[132:135], v[184:187], v[96:99]
	v_mfma_f32_16x16x32_bf16 v[88:91], v[140:143], v[184:187], v[88:91]
	v_mfma_f32_16x16x32_bf16 v[80:83], v[132:135], v[192:195], v[80:83]
	v_mfma_f32_16x16x32_bf16 v[72:75], v[140:143], v[192:195], v[72:75]
	s_setprio 0
	s_barrier
	s_add_i32 s71, s65, s54
	v_lshl_add_u64 v[160:161], s[44:45], 0, v[146:147]
	s_mov_b32 m0, s71
	ds_read_b128 v[196:199], v167
	ds_read_b128 v[200:203], v167 offset:1024
	ds_read_b128 v[204:207], v167 offset:2048
	ds_read_b128 v[208:211], v167 offset:3072
	global_load_lds_dwordx4 v[160:161], off
	v_lshl_add_u64 v[212:213], s[44:45], 0, v[148:149]
	s_add_i32 m0, s71, 0x2000
	s_nop 0
	global_load_lds_dwordx4 v[212:213], off
	s_barrier
	s_waitcnt lgkmcnt(0)
	s_setprio 1
	s_waitcnt lgkmcnt(0)
	v_mfma_f32_16x16x32_bf16 v[116:119], v[196:199], v[156:159], 0
	v_mfma_f32_16x16x32_bf16 v[108:111], v[204:207], v[156:159], 0
	v_mfma_f32_16x16x32_bf16 v[100:103], v[196:199], v[172:175], 0
	v_mfma_f32_16x16x32_bf16 v[92:95], v[204:207], v[172:175], 0
	v_mfma_f32_16x16x32_bf16 v[84:87], v[196:199], v[180:183], 0
	v_mfma_f32_16x16x32_bf16 v[76:79], v[204:207], v[180:183], 0
	v_mfma_f32_16x16x32_bf16 v[68:71], v[196:199], v[188:191], 0
	v_mfma_f32_16x16x32_bf16 v[64:67], v[204:207], v[188:191], 0
	v_mfma_f32_16x16x32_bf16 v[116:119], v[200:203], v[168:171], v[116:119]
	v_mfma_f32_16x16x32_bf16 v[108:111], v[208:211], v[168:171], v[108:111]
	v_mfma_f32_16x16x32_bf16 v[100:103], v[200:203], v[176:179], v[100:103]
	v_mfma_f32_16x16x32_bf16 v[92:95], v[208:211], v[176:179], v[92:95]
	v_mfma_f32_16x16x32_bf16 v[84:87], v[200:203], v[184:187], v[84:87]
	v_mfma_f32_16x16x32_bf16 v[76:79], v[208:211], v[184:187], v[76:79]
	v_mfma_f32_16x16x32_bf16 v[68:71], v[200:203], v[192:195], v[68:71]
	v_mfma_f32_16x16x32_bf16 v[64:67], v[208:211], v[192:195], v[64:67]
	s_setprio 0
	s_mov_b32 m0, s41
	v_lshl_add_u64 v[214:215], s[46:47], 0, v[146:147]
	s_barrier
	ds_read_b128 v[156:159], v166 offset:16384
	ds_read_b128 v[168:171], v166 offset:17408
	ds_read_b128 v[172:175], v166 offset:18432
	ds_read_b128 v[176:179], v166 offset:19456
	ds_read_b128 v[180:183], v166 offset:20480
	ds_read_b128 v[184:187], v166 offset:21504
	ds_read_b128 v[188:191], v166 offset:22528
	ds_read_b128 v[192:195], v166 offset:23552
	global_load_lds_dwordx4 v[214:215], off
	v_lshl_add_u64 v[216:217], s[46:47], 0, v[148:149]
	s_mov_b32 m0, s55
	s_nop 0
	global_load_lds_dwordx4 v[216:217], off
	s_barrier
	s_waitcnt lgkmcnt(0)
	s_setprio 1
	s_waitcnt lgkmcnt(0)
	v_mfma_f32_16x16x32_bf16 v[60:63], v[128:131], v[156:159], 0
	v_mfma_f32_16x16x32_bf16 v[56:59], v[136:139], v[156:159], 0
	v_mfma_f32_16x16x32_bf16 v[48:51], v[128:131], v[172:175], 0
	v_mfma_f32_16x16x32_bf16 v[40:43], v[136:139], v[172:175], 0
	v_mfma_f32_16x16x32_bf16 v[32:35], v[128:131], v[180:183], 0
	v_mfma_f32_16x16x32_bf16 v[24:27], v[136:139], v[180:183], 0
	v_mfma_f32_16x16x32_bf16 v[16:19], v[128:131], v[188:191], 0
	v_mfma_f32_16x16x32_bf16 v[8:11], v[136:139], v[188:191], 0
	v_mfma_f32_16x16x32_bf16 v[60:63], v[132:135], v[168:171], v[60:63]
	v_mfma_f32_16x16x32_bf16 v[56:59], v[140:143], v[168:171], v[56:59]
	v_mfma_f32_16x16x32_bf16 v[48:51], v[132:135], v[176:179], v[48:51]
	v_mfma_f32_16x16x32_bf16 v[40:43], v[140:143], v[176:179], v[40:43]
	v_mfma_f32_16x16x32_bf16 v[32:35], v[132:135], v[184:187], v[32:35]
	v_mfma_f32_16x16x32_bf16 v[24:27], v[140:143], v[184:187], v[24:27]
	v_mfma_f32_16x16x32_bf16 v[16:19], v[132:135], v[192:195], v[16:19]
	v_mfma_f32_16x16x32_bf16 v[8:11], v[140:143], v[192:195], v[8:11]
	s_setprio 0
	s_barrier
	s_add_u32 s72, s44, 0x80000
	s_addc_u32 s73, s45, 0
	s_add_i32 s71, s66, s54
	v_lshl_add_u64 v[128:129], s[72:73], 0, v[146:147]
	s_mov_b32 m0, s71
	s_nop 0
	global_load_lds_dwordx4 v[128:129], off
	v_lshl_add_u64 v[128:129], s[72:73], 0, v[148:149]
	s_add_i32 m0, s71, 0x2000
	s_nop 0
	global_load_lds_dwordx4 v[128:129], off
	s_waitcnt vmcnt(6)
	s_barrier
	s_setprio 1
	v_mfma_f32_16x16x32_bf16 v[52:55], v[196:199], v[156:159], 0
	v_mfma_f32_16x16x32_bf16 v[44:47], v[204:207], v[156:159], 0
	v_mfma_f32_16x16x32_bf16 v[36:39], v[196:199], v[172:175], 0
	v_mfma_f32_16x16x32_bf16 v[28:31], v[204:207], v[172:175], 0
	v_mfma_f32_16x16x32_bf16 v[20:23], v[196:199], v[180:183], 0
	v_mfma_f32_16x16x32_bf16 v[12:15], v[204:207], v[180:183], 0
	v_mfma_f32_16x16x32_bf16 v[4:7], v[196:199], v[188:191], 0
	v_mfma_f32_16x16x32_bf16 v[0:3], v[204:207], v[188:191], 0
	v_mfma_f32_16x16x32_bf16 v[52:55], v[200:203], v[168:171], v[52:55]
	v_mfma_f32_16x16x32_bf16 v[44:47], v[208:211], v[168:171], v[44:47]
	v_mfma_f32_16x16x32_bf16 v[36:39], v[200:203], v[176:179], v[36:39]
	v_mfma_f32_16x16x32_bf16 v[28:31], v[208:211], v[176:179], v[28:31]
	v_mfma_f32_16x16x32_bf16 v[20:23], v[200:203], v[184:187], v[20:23]
	v_mfma_f32_16x16x32_bf16 v[12:15], v[208:211], v[184:187], v[12:15]
	v_mfma_f32_16x16x32_bf16 v[4:7], v[200:203], v[192:195], v[4:7]
	v_mfma_f32_16x16x32_bf16 v[0:3], v[208:211], v[192:195], v[0:3]
	s_setprio 0
	s_add_i32 s71, 0, 0x18000
	v_add_u32_e32 v140, s71, v163
	s_barrier
	ds_read_b128 v[128:131], v140
	ds_read_b128 v[132:135], v140 offset:1024
	ds_read_b128 v[136:139], v140 offset:2048
	ds_read_b128 v[140:143], v140 offset:3072
	s_add_u32 s46, s46, 0x80000
	s_addc_u32 s47, s47, 0
	s_mov_b32 m0, s56
	v_lshl_add_u64 v[196:197], s[46:47], 0, v[146:147]
	ds_read_b128 v[156:159], v166 offset:32768
	ds_read_b128 v[168:171], v166 offset:33792
	ds_read_b128 v[172:175], v166 offset:34816
	ds_read_b128 v[176:179], v166 offset:35840
	ds_read_b128 v[180:183], v166 offset:36864
	ds_read_b128 v[184:187], v166 offset:37888
	ds_read_b128 v[188:191], v166 offset:38912
	ds_read_b128 v[192:195], v166 offset:39936
	global_load_lds_dwordx4 v[196:197], off
	v_lshl_add_u64 v[196:197], s[46:47], 0, v[148:149]
	s_mov_b32 m0, s57
	s_nop 0
	global_load_lds_dwordx4 v[196:197], off
	s_waitcnt lgkmcnt(8)
	s_barrier
	s_waitcnt lgkmcnt(0)
	s_setprio 1
	s_waitcnt lgkmcnt(0)
	v_mfma_f32_16x16x32_bf16 v[124:127], v[128:131], v[156:159], v[124:127]
	v_mfma_f32_16x16x32_bf16 v[120:123], v[136:139], v[156:159], v[120:123]
	v_mfma_f32_16x16x32_bf16 v[112:115], v[128:131], v[172:175], v[112:115]
	v_mfma_f32_16x16x32_bf16 v[104:107], v[136:139], v[172:175], v[104:107]
	v_mfma_f32_16x16x32_bf16 v[96:99], v[128:131], v[180:183], v[96:99]
	v_mfma_f32_16x16x32_bf16 v[88:91], v[136:139], v[180:183], v[88:91]
	v_mfma_f32_16x16x32_bf16 v[80:83], v[128:131], v[188:191], v[80:83]
	v_mfma_f32_16x16x32_bf16 v[72:75], v[136:139], v[188:191], v[72:75]
	v_mfma_f32_16x16x32_bf16 v[124:127], v[132:135], v[168:171], v[124:127]
	v_mfma_f32_16x16x32_bf16 v[120:123], v[140:143], v[168:171], v[120:123]
	v_mfma_f32_16x16x32_bf16 v[112:115], v[132:135], v[176:179], v[112:115]
	v_mfma_f32_16x16x32_bf16 v[104:107], v[140:143], v[176:179], v[104:107]
	v_mfma_f32_16x16x32_bf16 v[96:99], v[132:135], v[184:187], v[96:99]
	v_mfma_f32_16x16x32_bf16 v[88:91], v[140:143], v[184:187], v[88:91]
	v_mfma_f32_16x16x32_bf16 v[80:83], v[132:135], v[192:195], v[80:83]
	v_mfma_f32_16x16x32_bf16 v[72:75], v[140:143], v[192:195], v[72:75]
	s_setprio 0
	s_barrier
	s_add_i32 s46, 0, 0x1c000
	s_add_i32 s47, s71, s54
	v_add_u32_e32 v208, s46, v163
	v_lshl_add_u64 v[160:161], v[160:161], 0, s[8:9]
	s_mov_b32 m0, s47
	ds_read_b128 v[196:199], v208
	ds_read_b128 v[200:203], v208 offset:1024
	ds_read_b128 v[204:207], v208 offset:2048
	ds_read_b128 v[208:211], v208 offset:3072
	global_load_lds_dwordx4 v[160:161], off
	v_lshl_add_u64 v[160:161], v[212:213], 0, s[8:9]
	s_add_i32 m0, s47, 0x2000
	s_nop 0
	global_load_lds_dwordx4 v[160:161], off
	s_barrier
	s_waitcnt lgkmcnt(0)
	s_setprio 1
	s_waitcnt lgkmcnt(0)
	v_mfma_f32_16x16x32_bf16 v[116:119], v[196:199], v[156:159], v[116:119]
	v_mfma_f32_16x16x32_bf16 v[108:111], v[204:207], v[156:159], v[108:111]
	v_mfma_f32_16x16x32_bf16 v[100:103], v[196:199], v[172:175], v[100:103]
	v_mfma_f32_16x16x32_bf16 v[92:95], v[204:207], v[172:175], v[92:95]
	v_mfma_f32_16x16x32_bf16 v[84:87], v[196:199], v[180:183], v[84:87]
	v_mfma_f32_16x16x32_bf16 v[76:79], v[204:207], v[180:183], v[76:79]
	v_mfma_f32_16x16x32_bf16 v[68:71], v[196:199], v[188:191], v[68:71]
	v_mfma_f32_16x16x32_bf16 v[64:67], v[204:207], v[188:191], v[64:67]
	v_mfma_f32_16x16x32_bf16 v[116:119], v[200:203], v[168:171], v[116:119]
	v_mfma_f32_16x16x32_bf16 v[108:111], v[208:211], v[168:171], v[108:111]
	v_mfma_f32_16x16x32_bf16 v[100:103], v[200:203], v[176:179], v[100:103]
	v_mfma_f32_16x16x32_bf16 v[92:95], v[208:211], v[176:179], v[92:95]
	v_mfma_f32_16x16x32_bf16 v[84:87], v[200:203], v[184:187], v[84:87]
	v_mfma_f32_16x16x32_bf16 v[76:79], v[208:211], v[184:187], v[76:79]
	v_mfma_f32_16x16x32_bf16 v[68:71], v[200:203], v[192:195], v[68:71]
	v_mfma_f32_16x16x32_bf16 v[64:67], v[208:211], v[192:195], v[64:67]
	s_setprio 0
	s_mov_b32 m0, s61
	v_lshl_add_u64 v[160:161], v[214:215], 0, s[8:9]
	s_barrier
	ds_read_b128 v[156:159], v166 offset:49152
	ds_read_b128 v[168:171], v166 offset:50176
	ds_read_b128 v[172:175], v166 offset:51200
	ds_read_b128 v[176:179], v166 offset:52224
	ds_read_b128 v[180:183], v166 offset:53248
	ds_read_b128 v[184:187], v166 offset:54272
	ds_read_b128 v[188:191], v166 offset:55296
	ds_read_b128 v[192:195], v166 offset:56320
	global_load_lds_dwordx4 v[160:161], off
	v_lshl_add_u64 v[160:161], v[216:217], 0, s[8:9]
	s_mov_b32 m0, s62
	s_nop 0
	global_load_lds_dwordx4 v[160:161], off
	s_barrier
	s_waitcnt lgkmcnt(0)
	s_setprio 1
	s_waitcnt lgkmcnt(0)
	v_mfma_f32_16x16x32_bf16 v[60:63], v[128:131], v[156:159], v[60:63]
	v_mfma_f32_16x16x32_bf16 v[56:59], v[136:139], v[156:159], v[56:59]
	v_mfma_f32_16x16x32_bf16 v[48:51], v[128:131], v[172:175], v[48:51]
	v_mfma_f32_16x16x32_bf16 v[40:43], v[136:139], v[172:175], v[40:43]
	v_mfma_f32_16x16x32_bf16 v[32:35], v[128:131], v[180:183], v[32:35]
	v_mfma_f32_16x16x32_bf16 v[24:27], v[136:139], v[180:183], v[24:27]
	v_mfma_f32_16x16x32_bf16 v[16:19], v[128:131], v[188:191], v[16:19]
	v_mfma_f32_16x16x32_bf16 v[8:11], v[136:139], v[188:191], v[8:11]
	v_mfma_f32_16x16x32_bf16 v[60:63], v[132:135], v[168:171], v[60:63]
	v_mfma_f32_16x16x32_bf16 v[56:59], v[140:143], v[168:171], v[56:59]
	v_mfma_f32_16x16x32_bf16 v[48:51], v[132:135], v[176:179], v[48:51]
	v_mfma_f32_16x16x32_bf16 v[40:43], v[140:143], v[176:179], v[40:43]
	v_mfma_f32_16x16x32_bf16 v[32:35], v[132:135], v[184:187], v[32:35]
	v_mfma_f32_16x16x32_bf16 v[24:27], v[140:143], v[184:187], v[24:27]
	v_mfma_f32_16x16x32_bf16 v[16:19], v[132:135], v[192:195], v[16:19]
	v_mfma_f32_16x16x32_bf16 v[8:11], v[140:143], v[192:195], v[8:11]
	s_setprio 0
	s_barrier
	s_add_u32 s44, s44, 0x80080
	s_addc_u32 s45, s45, 0
	s_add_i32 s46, s46, s54
	v_lshl_add_u64 v[128:129], s[44:45], 0, v[146:147]
	s_mov_b32 m0, s46
	s_nop 0
	global_load_lds_dwordx4 v[128:129], off
	v_lshl_add_u64 v[128:129], s[44:45], 0, v[148:149]
	s_add_i32 m0, s46, 0x2000
	s_nop 0
	global_load_lds_dwordx4 v[128:129], off
	s_waitcnt vmcnt(6)
	s_barrier
	s_setprio 1
	v_mfma_f32_16x16x32_bf16 v[52:55], v[196:199], v[156:159], v[52:55]
	v_mfma_f32_16x16x32_bf16 v[44:47], v[204:207], v[156:159], v[44:47]
	v_mfma_f32_16x16x32_bf16 v[36:39], v[196:199], v[172:175], v[36:39]
	v_mfma_f32_16x16x32_bf16 v[28:31], v[204:207], v[172:175], v[28:31]
	v_mfma_f32_16x16x32_bf16 v[20:23], v[196:199], v[180:183], v[20:23]
	v_mfma_f32_16x16x32_bf16 v[12:15], v[204:207], v[180:183], v[12:15]
	v_mfma_f32_16x16x32_bf16 v[4:7], v[196:199], v[188:191], v[4:7]
	v_mfma_f32_16x16x32_bf16 v[0:3], v[204:207], v[188:191], v[0:3]
	v_mfma_f32_16x16x32_bf16 v[52:55], v[200:203], v[168:171], v[52:55]
	v_mfma_f32_16x16x32_bf16 v[44:47], v[208:211], v[168:171], v[44:47]
	v_mfma_f32_16x16x32_bf16 v[36:39], v[200:203], v[176:179], v[36:39]
	v_mfma_f32_16x16x32_bf16 v[28:31], v[208:211], v[176:179], v[28:31]
	v_mfma_f32_16x16x32_bf16 v[20:23], v[200:203], v[184:187], v[20:23]
	v_mfma_f32_16x16x32_bf16 v[12:15], v[208:211], v[184:187], v[12:15]
	v_mfma_f32_16x16x32_bf16 v[4:7], v[200:203], v[192:195], v[4:7]
	v_mfma_f32_16x16x32_bf16 v[0:3], v[208:211], v[192:195], v[0:3]
	s_setprio 0
	s_add_i32 s70, s70, 2
	s_add_u32 s42, s42, 0x100
	s_addc_u32 s43, s43, 0
	s_add_u32 s29, s29, 0x100
	s_addc_u32 s69, s69, 0
	s_cmp_gt_u32 s70, 29
	s_barrier
	s_cbranch_scc0 .LBB0_1074

.LBB0_1202:
	s_ashr_i32 s13, s12, 31
	s_xor_b64 s[16:17], s[28:29], -1
	s_lshl_b64 s[14:15], s[12:13], 20
	s_add_u32 s14, s33, s14
	s_addc_u32 s15, s40, s15
	s_and_b64 s[18:19], s[28:29], exec
	s_cselect_b32 s13, s15, s35
	s_cselect_b32 s58, s14, s34
	s_ashr_i32 s11, s10, 31
	s_lshl_b64 s[18:19], s[10:11], 20
	s_add_u32 s18, s41, s18
	s_addc_u32 s19, s42, s19
	s_and_b64 s[28:29], s[28:29], exec
	s_cselect_b32 s11, s19, s37
	s_cselect_b32 s28, s18, s36
	s_add_u32 s34, s34, 0x80080
	s_addc_u32 s35, s35, 0
	s_add_u32 s29, s36, 0x100
	s_addc_u32 s59, s37, 0
	s_mov_b32 s60, -2
	ds_read_b128 v[150:153], v147
	ds_read_b128 v[154:157], v147 offset:1024
	ds_read_b128 v[158:161], v147 offset:2048
	ds_read_b128 v[162:165], v147 offset:3072
	s_add_u32 s36, s34, 0xfff80080
	s_addc_u32 s37, s35, -1
	s_cmp_eq_u32 s60, 28
	s_cselect_b32 s39, s13, s37
	s_cselect_b32 s38, s58, s36
	s_cselect_b32 s37, s11, s59
	s_cselect_b32 s36, s28, s29
	v_lshl_add_u64 v[198:199], s[34:35], 0, v[136:137]
	s_add_i32 m0, s31, 0xc000
	ds_read_b128 v[166:169], v148
	ds_read_b128 v[170:173], v148 offset:1024
	ds_read_b128 v[174:177], v148 offset:2048
	ds_read_b128 v[178:181], v148 offset:3072
	ds_read_b128 v[182:185], v148 offset:4096
	ds_read_b128 v[186:189], v148 offset:5120
	ds_read_b128 v[190:193], v148 offset:6144
	ds_read_b128 v[194:197], v148 offset:7168
	global_load_lds_dwordx4 v[198:199], off
	v_lshl_add_u64 v[198:199], s[34:35], 0, v[138:139]
	s_add_i32 m0, s31, 0xe000
	s_nop 0
	global_load_lds_dwordx4 v[198:199], off
	s_waitcnt lgkmcnt(8)
	s_barrier
	s_waitcnt lgkmcnt(0)
	s_setprio 1
	s_waitcnt lgkmcnt(0)
	v_mfma_f32_16x16x32_bf16 v[124:127], v[150:153], v[166:169], 0
	v_mfma_f32_16x16x32_bf16 v[120:123], v[158:161], v[166:169], 0
	v_mfma_f32_16x16x32_bf16 v[108:111], v[150:153], v[174:177], 0
	v_mfma_f32_16x16x32_bf16 v[104:107], v[158:161], v[174:177], 0
	v_mfma_f32_16x16x32_bf16 v[92:95], v[150:153], v[182:185], 0
	v_mfma_f32_16x16x32_bf16 v[88:91], v[158:161], v[182:185], 0
	v_mfma_f32_16x16x32_bf16 v[76:79], v[150:153], v[190:193], 0
	v_mfma_f32_16x16x32_bf16 v[72:75], v[158:161], v[190:193], 0
	v_mfma_f32_16x16x32_bf16 v[124:127], v[154:157], v[170:173], v[124:127]
	v_mfma_f32_16x16x32_bf16 v[120:123], v[162:165], v[170:173], v[120:123]
	v_mfma_f32_16x16x32_bf16 v[108:111], v[154:157], v[178:181], v[108:111]
	v_mfma_f32_16x16x32_bf16 v[104:107], v[162:165], v[178:181], v[104:107]
	v_mfma_f32_16x16x32_bf16 v[92:95], v[154:157], v[186:189], v[92:95]
	v_mfma_f32_16x16x32_bf16 v[88:91], v[162:165], v[186:189], v[88:91]
	v_mfma_f32_16x16x32_bf16 v[76:79], v[154:157], v[194:197], v[76:79]
	v_mfma_f32_16x16x32_bf16 v[72:75], v[162:165], v[194:197], v[72:75]
	s_setprio 0
	s_barrier
	s_add_i32 s61, s54, s43
	v_lshl_add_u64 v[214:215], s[36:37], 0, v[132:133]
	s_mov_b32 m0, s61
	ds_read_b128 v[198:201], v149
	ds_read_b128 v[202:205], v149 offset:1024
	ds_read_b128 v[206:209], v149 offset:2048
	ds_read_b128 v[210:213], v149 offset:3072
	global_load_lds_dwordx4 v[214:215], off
	v_lshl_add_u64 v[216:217], s[36:37], 0, v[128:129]
	s_add_i32 m0, s61, 0x2000
	s_nop 0
	global_load_lds_dwordx4 v[216:217], off
	s_barrier
	s_waitcnt lgkmcnt(0)
	s_setprio 1
	s_waitcnt lgkmcnt(0)
	v_mfma_f32_16x16x32_bf16 v[116:119], v[198:201], v[166:169], 0
	v_mfma_f32_16x16x32_bf16 v[112:115], v[206:209], v[166:169], 0
	v_mfma_f32_16x16x32_bf16 v[100:103], v[198:201], v[174:177], 0
	v_mfma_f32_16x16x32_bf16 v[96:99], v[206:209], v[174:177], 0
	v_mfma_f32_16x16x32_bf16 v[84:87], v[198:201], v[182:185], 0
	v_mfma_f32_16x16x32_bf16 v[80:83], v[206:209], v[182:185], 0
	v_mfma_f32_16x16x32_bf16 v[68:71], v[198:201], v[190:193], 0
	v_mfma_f32_16x16x32_bf16 v[64:67], v[206:209], v[190:193], 0
	v_mfma_f32_16x16x32_bf16 v[116:119], v[202:205], v[170:173], v[116:119]
	v_mfma_f32_16x16x32_bf16 v[112:115], v[210:213], v[170:173], v[112:115]
	v_mfma_f32_16x16x32_bf16 v[100:103], v[202:205], v[178:181], v[100:103]
	v_mfma_f32_16x16x32_bf16 v[96:99], v[210:213], v[178:181], v[96:99]
	v_mfma_f32_16x16x32_bf16 v[84:87], v[202:205], v[186:189], v[84:87]
	v_mfma_f32_16x16x32_bf16 v[80:83], v[210:213], v[186:189], v[80:83]
	v_mfma_f32_16x16x32_bf16 v[68:71], v[202:205], v[194:197], v[68:71]
	v_mfma_f32_16x16x32_bf16 v[64:67], v[210:213], v[194:197], v[64:67]
	s_setprio 0
	s_mov_b32 m0, s31
	v_lshl_add_u64 v[218:219], s[38:39], 0, v[134:135]
	s_barrier
	ds_read_b128 v[166:169], v148 offset:16384
	ds_read_b128 v[170:173], v148 offset:17408
	ds_read_b128 v[174:177], v148 offset:18432
	ds_read_b128 v[178:181], v148 offset:19456
	ds_read_b128 v[182:185], v148 offset:20480
	ds_read_b128 v[186:189], v148 offset:21504
	ds_read_b128 v[190:193], v148 offset:22528
	ds_read_b128 v[194:197], v148 offset:23552
	global_load_lds_dwordx4 v[218:219], off
	v_lshl_add_u64 v[220:221], s[38:39], 0, v[130:131]
	s_mov_b32 m0, s46
	s_nop 0
	global_load_lds_dwordx4 v[220:221], off
	s_barrier
	s_waitcnt lgkmcnt(0)
	s_setprio 1
	s_waitcnt lgkmcnt(0)
	v_mfma_f32_16x16x32_bf16 v[60:63], v[150:153], v[166:169], 0
	v_mfma_f32_16x16x32_bf16 v[56:59], v[158:161], v[166:169], 0
	v_mfma_f32_16x16x32_bf16 v[44:47], v[150:153], v[174:177], 0
	v_mfma_f32_16x16x32_bf16 v[40:43], v[158:161], v[174:177], 0
	v_mfma_f32_16x16x32_bf16 v[28:31], v[150:153], v[182:185], 0
	v_mfma_f32_16x16x32_bf16 v[24:27], v[158:161], v[182:185], 0
	v_mfma_f32_16x16x32_bf16 v[12:15], v[150:153], v[190:193], 0
	v_mfma_f32_16x16x32_bf16 v[8:11], v[158:161], v[190:193], 0
	v_mfma_f32_16x16x32_bf16 v[60:63], v[154:157], v[170:173], v[60:63]
	v_mfma_f32_16x16x32_bf16 v[56:59], v[162:165], v[170:173], v[56:59]
	v_mfma_f32_16x16x32_bf16 v[44:47], v[154:157], v[178:181], v[44:47]
	v_mfma_f32_16x16x32_bf16 v[40:43], v[162:165], v[178:181], v[40:43]
	v_mfma_f32_16x16x32_bf16 v[28:31], v[154:157], v[186:189], v[28:31]
	v_mfma_f32_16x16x32_bf16 v[24:27], v[162:165], v[186:189], v[24:27]
	v_mfma_f32_16x16x32_bf16 v[12:15], v[154:157], v[194:197], v[12:15]
	v_mfma_f32_16x16x32_bf16 v[8:11], v[162:165], v[194:197], v[8:11]
	s_setprio 0
	s_barrier
	s_add_u32 s62, s36, 0x80000
	s_addc_u32 s63, s37, 0
	s_add_i32 s61, s55, s43
	v_lshl_add_u64 v[150:151], s[62:63], 0, v[132:133]
	s_mov_b32 m0, s61
	s_nop 0
	global_load_lds_dwordx4 v[150:151], off
	v_lshl_add_u64 v[150:151], s[62:63], 0, v[128:129]
	s_add_i32 m0, s61, 0x2000
	s_nop 0
	global_load_lds_dwordx4 v[150:151], off
	s_waitcnt vmcnt(6)
	s_barrier
	s_setprio 1
	v_mfma_f32_16x16x32_bf16 v[52:55], v[198:201], v[166:169], 0
	v_mfma_f32_16x16x32_bf16 v[48:51], v[206:209], v[166:169], 0
	v_mfma_f32_16x16x32_bf16 v[36:39], v[198:201], v[174:177], 0
	v_mfma_f32_16x16x32_bf16 v[32:35], v[206:209], v[174:177], 0
	v_mfma_f32_16x16x32_bf16 v[20:23], v[198:201], v[182:185], 0
	v_mfma_f32_16x16x32_bf16 v[16:19], v[206:209], v[182:185], 0
	v_mfma_f32_16x16x32_bf16 v[4:7], v[198:201], v[190:193], 0
	v_mfma_f32_16x16x32_bf16 v[0:3], v[206:209], v[190:193], 0
	v_mfma_f32_16x16x32_bf16 v[52:55], v[202:205], v[170:173], v[52:55]
	v_mfma_f32_16x16x32_bf16 v[48:51], v[210:213], v[170:173], v[48:51]
	v_mfma_f32_16x16x32_bf16 v[36:39], v[202:205], v[178:181], v[36:39]
	v_mfma_f32_16x16x32_bf16 v[32:35], v[210:213], v[178:181], v[32:35]
	v_mfma_f32_16x16x32_bf16 v[20:23], v[202:205], v[186:189], v[20:23]
	v_mfma_f32_16x16x32_bf16 v[16:19], v[210:213], v[186:189], v[16:19]
	v_mfma_f32_16x16x32_bf16 v[4:7], v[202:205], v[194:197], v[4:7]
	v_mfma_f32_16x16x32_bf16 v[0:3], v[210:213], v[194:197], v[0:3]
	s_setprio 0
	s_add_i32 s61, 0, 0x18000
	v_add_u32_e32 v162, s61, v143
	s_barrier
	ds_read_b128 v[150:153], v162
	ds_read_b128 v[154:157], v162 offset:1024
	ds_read_b128 v[158:161], v162 offset:2048
	ds_read_b128 v[162:165], v162 offset:3072
	s_add_u32 s38, s38, 0x80000
	s_addc_u32 s39, s39, 0
	s_mov_b32 m0, s47
	v_lshl_add_u64 v[198:199], s[38:39], 0, v[134:135]
	ds_read_b128 v[166:169], v148 offset:32768
	ds_read_b128 v[170:173], v148 offset:33792
	ds_read_b128 v[174:177], v148 offset:34816
	ds_read_b128 v[178:181], v148 offset:35840
	ds_read_b128 v[182:185], v148 offset:36864
	ds_read_b128 v[186:189], v148 offset:37888
	ds_read_b128 v[190:193], v148 offset:38912
	ds_read_b128 v[194:197], v148 offset:39936
	global_load_lds_dwordx4 v[198:199], off
	v_lshl_add_u64 v[198:199], s[38:39], 0, v[130:131]
	s_mov_b32 m0, s48
	s_nop 0
	global_load_lds_dwordx4 v[198:199], off
	s_waitcnt lgkmcnt(8)
	s_barrier
	s_waitcnt lgkmcnt(0)
	s_setprio 1
	s_waitcnt lgkmcnt(0)
	v_mfma_f32_16x16x32_bf16 v[124:127], v[150:153], v[166:169], v[124:127]
	v_mfma_f32_16x16x32_bf16 v[120:123], v[158:161], v[166:169], v[120:123]
	v_mfma_f32_16x16x32_bf16 v[108:111], v[150:153], v[174:177], v[108:111]
	v_mfma_f32_16x16x32_bf16 v[104:107], v[158:161], v[174:177], v[104:107]
	v_mfma_f32_16x16x32_bf16 v[92:95], v[150:153], v[182:185], v[92:95]
	v_mfma_f32_16x16x32_bf16 v[88:91], v[158:161], v[182:185], v[88:91]
	v_mfma_f32_16x16x32_bf16 v[76:79], v[150:153], v[190:193], v[76:79]
	v_mfma_f32_16x16x32_bf16 v[72:75], v[158:161], v[190:193], v[72:75]
	v_mfma_f32_16x16x32_bf16 v[124:127], v[154:157], v[170:173], v[124:127]
	v_mfma_f32_16x16x32_bf16 v[120:123], v[162:165], v[170:173], v[120:123]
	v_mfma_f32_16x16x32_bf16 v[108:111], v[154:157], v[178:181], v[108:111]
	v_mfma_f32_16x16x32_bf16 v[104:107], v[162:165], v[178:181], v[104:107]
	v_mfma_f32_16x16x32_bf16 v[92:95], v[154:157], v[186:189], v[92:95]
	v_mfma_f32_16x16x32_bf16 v[88:91], v[162:165], v[186:189], v[88:91]
	v_mfma_f32_16x16x32_bf16 v[76:79], v[154:157], v[194:197], v[76:79]
	v_mfma_f32_16x16x32_bf16 v[72:75], v[162:165], v[194:197], v[72:75]
	s_setprio 0
	s_barrier
	s_add_i32 s38, 0, 0x1c000
	s_add_i32 s39, s61, s43
	v_add_u32_e32 v210, s38, v143
	v_lshl_add_u64 v[214:215], v[214:215], 0, s[8:9]
	s_mov_b32 m0, s39
	ds_read_b128 v[198:201], v210
	ds_read_b128 v[202:205], v210 offset:1024
	ds_read_b128 v[206:209], v210 offset:2048
	ds_read_b128 v[210:213], v210 offset:3072
	global_load_lds_dwordx4 v[214:215], off
	v_lshl_add_u64 v[214:215], v[216:217], 0, s[8:9]
	s_add_i32 m0, s39, 0x2000
	s_nop 0
	global_load_lds_dwordx4 v[214:215], off
	s_barrier
	s_waitcnt lgkmcnt(0)
	s_setprio 1
	s_waitcnt lgkmcnt(0)
	v_mfma_f32_16x16x32_bf16 v[116:119], v[198:201], v[166:169], v[116:119]
	v_mfma_f32_16x16x32_bf16 v[112:115], v[206:209], v[166:169], v[112:115]
	v_mfma_f32_16x16x32_bf16 v[100:103], v[198:201], v[174:177], v[100:103]
	v_mfma_f32_16x16x32_bf16 v[96:99], v[206:209], v[174:177], v[96:99]
	v_mfma_f32_16x16x32_bf16 v[84:87], v[198:201], v[182:185], v[84:87]
	v_mfma_f32_16x16x32_bf16 v[80:83], v[206:209], v[182:185], v[80:83]
	v_mfma_f32_16x16x32_bf16 v[68:71], v[198:201], v[190:193], v[68:71]
	v_mfma_f32_16x16x32_bf16 v[64:67], v[206:209], v[190:193], v[64:67]
	v_mfma_f32_16x16x32_bf16 v[116:119], v[202:205], v[170:173], v[116:119]
	v_mfma_f32_16x16x32_bf16 v[112:115], v[210:213], v[170:173], v[112:115]
	v_mfma_f32_16x16x32_bf16 v[100:103], v[202:205], v[178:181], v[100:103]
	v_mfma_f32_16x16x32_bf16 v[96:99], v[210:213], v[178:181], v[96:99]
	v_mfma_f32_16x16x32_bf16 v[84:87], v[202:205], v[186:189], v[84:87]
	v_mfma_f32_16x16x32_bf16 v[80:83], v[210:213], v[186:189], v[80:83]
	v_mfma_f32_16x16x32_bf16 v[68:71], v[202:205], v[194:197], v[68:71]
	v_mfma_f32_16x16x32_bf16 v[64:67], v[210:213], v[194:197], v[64:67]
	s_setprio 0
	s_mov_b32 m0, s50
	v_lshl_add_u64 v[214:215], v[218:219], 0, s[8:9]
	s_barrier
	ds_read_b128 v[166:169], v148 offset:49152
	ds_read_b128 v[170:173], v148 offset:50176
	ds_read_b128 v[174:177], v148 offset:51200
	ds_read_b128 v[178:181], v148 offset:52224
	ds_read_b128 v[182:185], v148 offset:53248
	ds_read_b128 v[186:189], v148 offset:54272
	ds_read_b128 v[190:193], v148 offset:55296
	ds_read_b128 v[194:197], v148 offset:56320
	global_load_lds_dwordx4 v[214:215], off
	v_lshl_add_u64 v[214:215], v[220:221], 0, s[8:9]
	s_mov_b32 m0, s51
	s_nop 0
	global_load_lds_dwordx4 v[214:215], off
	s_barrier
	s_waitcnt lgkmcnt(0)
	s_setprio 1
	s_waitcnt lgkmcnt(0)
	v_mfma_f32_16x16x32_bf16 v[60:63], v[150:153], v[166:169], v[60:63]
	v_mfma_f32_16x16x32_bf16 v[56:59], v[158:161], v[166:169], v[56:59]
	v_mfma_f32_16x16x32_bf16 v[44:47], v[150:153], v[174:177], v[44:47]
	v_mfma_f32_16x16x32_bf16 v[40:43], v[158:161], v[174:177], v[40:43]
	v_mfma_f32_16x16x32_bf16 v[28:31], v[150:153], v[182:185], v[28:31]
	v_mfma_f32_16x16x32_bf16 v[24:27], v[158:161], v[182:185], v[24:27]
	v_mfma_f32_16x16x32_bf16 v[12:15], v[150:153], v[190:193], v[12:15]
	v_mfma_f32_16x16x32_bf16 v[8:11], v[158:161], v[190:193], v[8:11]
	v_mfma_f32_16x16x32_bf16 v[60:63], v[154:157], v[170:173], v[60:63]
	v_mfma_f32_16x16x32_bf16 v[56:59], v[162:165], v[170:173], v[56:59]
	v_mfma_f32_16x16x32_bf16 v[44:47], v[154:157], v[178:181], v[44:47]
	v_mfma_f32_16x16x32_bf16 v[40:43], v[162:165], v[178:181], v[40:43]
	v_mfma_f32_16x16x32_bf16 v[28:31], v[154:157], v[186:189], v[28:31]
	v_mfma_f32_16x16x32_bf16 v[24:27], v[162:165], v[186:189], v[24:27]
	v_mfma_f32_16x16x32_bf16 v[12:15], v[154:157], v[194:197], v[12:15]
	v_mfma_f32_16x16x32_bf16 v[8:11], v[162:165], v[194:197], v[8:11]
	s_setprio 0
	s_barrier
	s_add_u32 s36, s36, 0x80080
	s_addc_u32 s37, s37, 0
	s_add_i32 s38, s38, s43
	v_lshl_add_u64 v[150:151], s[36:37], 0, v[132:133]
	s_mov_b32 m0, s38
	s_nop 0
	global_load_lds_dwordx4 v[150:151], off
	v_lshl_add_u64 v[150:151], s[36:37], 0, v[128:129]
	s_add_i32 m0, s38, 0x2000
	s_nop 0
	global_load_lds_dwordx4 v[150:151], off
	s_waitcnt vmcnt(6)
	s_barrier
	s_setprio 1
	v_mfma_f32_16x16x32_bf16 v[52:55], v[198:201], v[166:169], v[52:55]
	v_mfma_f32_16x16x32_bf16 v[48:51], v[206:209], v[166:169], v[48:51]
	v_mfma_f32_16x16x32_bf16 v[36:39], v[198:201], v[174:177], v[36:39]
	v_mfma_f32_16x16x32_bf16 v[32:35], v[206:209], v[174:177], v[32:35]
	v_mfma_f32_16x16x32_bf16 v[20:23], v[198:201], v[182:185], v[20:23]
	v_mfma_f32_16x16x32_bf16 v[16:19], v[206:209], v[182:185], v[16:19]
	v_mfma_f32_16x16x32_bf16 v[4:7], v[198:201], v[190:193], v[4:7]
	v_mfma_f32_16x16x32_bf16 v[0:3], v[206:209], v[190:193], v[0:3]
	v_mfma_f32_16x16x32_bf16 v[52:55], v[202:205], v[170:173], v[52:55]
	v_mfma_f32_16x16x32_bf16 v[48:51], v[210:213], v[170:173], v[48:51]
	v_mfma_f32_16x16x32_bf16 v[36:39], v[202:205], v[178:181], v[36:39]
	v_mfma_f32_16x16x32_bf16 v[32:35], v[210:213], v[178:181], v[32:35]
	v_mfma_f32_16x16x32_bf16 v[20:23], v[202:205], v[186:189], v[20:23]
	v_mfma_f32_16x16x32_bf16 v[16:19], v[210:213], v[186:189], v[16:19]
	v_mfma_f32_16x16x32_bf16 v[4:7], v[202:205], v[194:197], v[4:7]
	v_mfma_f32_16x16x32_bf16 v[0:3], v[210:213], v[194:197], v[0:3]
	s_setprio 0
	s_add_i32 s60, s60, 2
	s_add_u32 s34, s34, 0x100
	s_addc_u32 s35, s35, 0
	s_add_u32 s29, s29, 0x100
	s_addc_u32 s59, s59, 0
	s_cmp_gt_u32 s60, 29
	s_barrier
	s_cbranch_scc0 .LBB0_1203

.LBB0_1284:
	s_add_u32 s36, s36, 0x160080
	s_addc_u32 s37, s37, 0
	s_add_u32 s28, s38, 0x100
	s_addc_u32 s29, s39, 0
	s_mov_b32 s68, -2
	ds_read_b128 v[128:131], v169
	ds_read_b128 v[132:135], v169 offset:1024
	ds_read_b128 v[136:139], v169 offset:2048
	ds_read_b128 v[140:143], v169 offset:3072
	s_add_u32 s38, s36, 0xffea0080
	s_addc_u32 s39, s37, -1
	s_cmpk_eq_i32 s68, 0x54
	s_cselect_b32 s41, s35, s39
	s_cselect_b32 s40, s34, s38
	s_cselect_b32 s39, s1, s29
	s_cselect_b32 s38, s0, s28
	v_lshl_add_u64 v[164:165], s[36:37], 0, v[150:151]
	s_add_i32 m0, s47, 0xc000
	ds_read_b128 v[156:159], v170
	ds_read_b128 v[160:163], v170 offset:1024
	ds_read_b128 v[172:175], v170 offset:2048
	ds_read_b128 v[176:179], v170 offset:3072
	ds_read_b128 v[180:183], v170 offset:4096
	ds_read_b128 v[184:187], v170 offset:5120
	ds_read_b128 v[188:191], v170 offset:6144
	ds_read_b128 v[192:195], v170 offset:7168
	global_load_lds_dwordx4 v[164:165], off
	v_lshl_add_u64 v[164:165], s[36:37], 0, v[152:153]
	s_add_i32 m0, s47, 0xe000
	s_nop 0
	global_load_lds_dwordx4 v[164:165], off
	s_waitcnt lgkmcnt(8)
	s_barrier
	s_waitcnt lgkmcnt(0)
	s_setprio 1
	s_waitcnt lgkmcnt(0)
	v_mfma_f32_16x16x32_bf16 v[124:127], v[128:131], v[156:159], 0
	v_mfma_f32_16x16x32_bf16 v[120:123], v[136:139], v[156:159], 0
	v_mfma_f32_16x16x32_bf16 v[116:119], v[128:131], v[172:175], 0
	v_mfma_f32_16x16x32_bf16 v[104:107], v[136:139], v[172:175], 0
	v_mfma_f32_16x16x32_bf16 v[92:95], v[128:131], v[180:183], 0
	v_mfma_f32_16x16x32_bf16 v[88:91], v[136:139], v[180:183], 0
	v_mfma_f32_16x16x32_bf16 v[76:79], v[128:131], v[188:191], 0
	v_mfma_f32_16x16x32_bf16 v[72:75], v[136:139], v[188:191], 0
	v_mfma_f32_16x16x32_bf16 v[124:127], v[132:135], v[160:163], v[124:127]
	v_mfma_f32_16x16x32_bf16 v[120:123], v[140:143], v[160:163], v[120:123]
	v_mfma_f32_16x16x32_bf16 v[116:119], v[132:135], v[176:179], v[116:119]
	v_mfma_f32_16x16x32_bf16 v[104:107], v[140:143], v[176:179], v[104:107]
	v_mfma_f32_16x16x32_bf16 v[92:95], v[132:135], v[184:187], v[92:95]
	v_mfma_f32_16x16x32_bf16 v[88:91], v[140:143], v[184:187], v[88:91]
	v_mfma_f32_16x16x32_bf16 v[76:79], v[132:135], v[192:195], v[76:79]
	v_mfma_f32_16x16x32_bf16 v[72:75], v[140:143], v[192:195], v[72:75]
	s_setprio 0
	s_barrier
	s_add_i32 s69, s58, s46
	v_lshl_add_u64 v[164:165], s[38:39], 0, v[146:147]
	s_mov_b32 m0, s69
	ds_read_b128 v[196:199], v171
	ds_read_b128 v[200:203], v171 offset:1024
	ds_read_b128 v[204:207], v171 offset:2048
	ds_read_b128 v[208:211], v171 offset:3072
	global_load_lds_dwordx4 v[164:165], off
	v_lshl_add_u64 v[212:213], s[38:39], 0, v[148:149]
	s_add_i32 m0, s69, 0x2000
	s_nop 0
	global_load_lds_dwordx4 v[212:213], off
	s_barrier
	s_waitcnt lgkmcnt(0)
	s_setprio 1
	s_waitcnt lgkmcnt(0)
	v_mfma_f32_16x16x32_bf16 v[112:115], v[196:199], v[156:159], 0
	v_mfma_f32_16x16x32_bf16 v[108:111], v[204:207], v[156:159], 0
	v_mfma_f32_16x16x32_bf16 v[100:103], v[196:199], v[172:175], 0
	v_mfma_f32_16x16x32_bf16 v[96:99], v[204:207], v[172:175], 0
	v_mfma_f32_16x16x32_bf16 v[84:87], v[196:199], v[180:183], 0
	v_mfma_f32_16x16x32_bf16 v[80:83], v[204:207], v[180:183], 0
	v_mfma_f32_16x16x32_bf16 v[68:71], v[196:199], v[188:191], 0
	v_mfma_f32_16x16x32_bf16 v[64:67], v[204:207], v[188:191], 0
	v_mfma_f32_16x16x32_bf16 v[112:115], v[200:203], v[160:163], v[112:115]
	v_mfma_f32_16x16x32_bf16 v[108:111], v[208:211], v[160:163], v[108:111]
	v_mfma_f32_16x16x32_bf16 v[100:103], v[200:203], v[176:179], v[100:103]
	v_mfma_f32_16x16x32_bf16 v[96:99], v[208:211], v[176:179], v[96:99]
	v_mfma_f32_16x16x32_bf16 v[84:87], v[200:203], v[184:187], v[84:87]
	v_mfma_f32_16x16x32_bf16 v[80:83], v[208:211], v[184:187], v[80:83]
	v_mfma_f32_16x16x32_bf16 v[68:71], v[200:203], v[192:195], v[68:71]
	v_mfma_f32_16x16x32_bf16 v[64:67], v[208:211], v[192:195], v[64:67]
	s_setprio 0
	s_mov_b32 m0, s47
	v_lshl_add_u64 v[214:215], s[40:41], 0, v[146:147]
	s_barrier
	ds_read_b128 v[156:159], v170 offset:16384
	ds_read_b128 v[160:163], v170 offset:17408
	ds_read_b128 v[172:175], v170 offset:18432
	ds_read_b128 v[176:179], v170 offset:19456
	ds_read_b128 v[180:183], v170 offset:20480
	ds_read_b128 v[184:187], v170 offset:21504
	ds_read_b128 v[188:191], v170 offset:22528
	ds_read_b128 v[192:195], v170 offset:23552
	global_load_lds_dwordx4 v[214:215], off
	v_lshl_add_u64 v[216:217], s[40:41], 0, v[148:149]
	s_mov_b32 m0, s48
	s_nop 0
	global_load_lds_dwordx4 v[216:217], off
	s_barrier
	s_waitcnt lgkmcnt(0)
	s_setprio 1
	s_waitcnt lgkmcnt(0)
	v_mfma_f32_16x16x32_bf16 v[60:63], v[128:131], v[156:159], 0
	v_mfma_f32_16x16x32_bf16 v[56:59], v[136:139], v[156:159], 0
	v_mfma_f32_16x16x32_bf16 v[44:47], v[128:131], v[172:175], 0
	v_mfma_f32_16x16x32_bf16 v[40:43], v[136:139], v[172:175], 0
	v_mfma_f32_16x16x32_bf16 v[36:39], v[128:131], v[180:183], 0
	v_mfma_f32_16x16x32_bf16 v[28:31], v[136:139], v[180:183], 0
	v_mfma_f32_16x16x32_bf16 v[20:23], v[128:131], v[188:191], 0
	v_mfma_f32_16x16x32_bf16 v[12:15], v[136:139], v[188:191], 0
	v_mfma_f32_16x16x32_bf16 v[60:63], v[132:135], v[160:163], v[60:63]
	v_mfma_f32_16x16x32_bf16 v[56:59], v[140:143], v[160:163], v[56:59]
	v_mfma_f32_16x16x32_bf16 v[44:47], v[132:135], v[176:179], v[44:47]
	v_mfma_f32_16x16x32_bf16 v[40:43], v[140:143], v[176:179], v[40:43]
	v_mfma_f32_16x16x32_bf16 v[36:39], v[132:135], v[184:187], v[36:39]
	v_mfma_f32_16x16x32_bf16 v[28:31], v[140:143], v[184:187], v[28:31]
	v_mfma_f32_16x16x32_bf16 v[20:23], v[132:135], v[192:195], v[20:23]
	v_mfma_f32_16x16x32_bf16 v[12:15], v[140:143], v[192:195], v[12:15]
	s_setprio 0
	s_barrier
	s_add_u32 s70, s38, 0x160000
	s_addc_u32 s71, s39, 0
	s_add_i32 s69, s59, s46
	v_lshl_add_u64 v[128:129], s[70:71], 0, v[146:147]
	s_mov_b32 m0, s69
	s_nop 0
	global_load_lds_dwordx4 v[128:129], off
	v_lshl_add_u64 v[128:129], s[70:71], 0, v[148:149]
	s_add_i32 m0, s69, 0x2000
	s_nop 0
	global_load_lds_dwordx4 v[128:129], off
	s_waitcnt vmcnt(6)
	s_barrier
	s_setprio 1
	v_mfma_f32_16x16x32_bf16 v[52:55], v[196:199], v[156:159], 0
	v_mfma_f32_16x16x32_bf16 v[48:51], v[204:207], v[156:159], 0
	v_mfma_f32_16x16x32_bf16 v[32:35], v[196:199], v[172:175], 0
	v_mfma_f32_16x16x32_bf16 v[24:27], v[204:207], v[172:175], 0
	v_mfma_f32_16x16x32_bf16 v[16:19], v[196:199], v[180:183], 0
	v_mfma_f32_16x16x32_bf16 v[8:11], v[204:207], v[180:183], 0
	v_mfma_f32_16x16x32_bf16 v[4:7], v[196:199], v[188:191], 0
	v_mfma_f32_16x16x32_bf16 v[0:3], v[204:207], v[188:191], 0
	v_mfma_f32_16x16x32_bf16 v[52:55], v[200:203], v[160:163], v[52:55]
	v_mfma_f32_16x16x32_bf16 v[48:51], v[208:211], v[160:163], v[48:51]
	v_mfma_f32_16x16x32_bf16 v[32:35], v[200:203], v[176:179], v[32:35]
	v_mfma_f32_16x16x32_bf16 v[24:27], v[208:211], v[176:179], v[24:27]
	v_mfma_f32_16x16x32_bf16 v[16:19], v[200:203], v[184:187], v[16:19]
	v_mfma_f32_16x16x32_bf16 v[8:11], v[208:211], v[184:187], v[8:11]
	v_mfma_f32_16x16x32_bf16 v[4:7], v[200:203], v[192:195], v[4:7]
	v_mfma_f32_16x16x32_bf16 v[0:3], v[208:211], v[192:195], v[0:3]
	s_setprio 0
	s_add_i32 s69, 0, 0x18000
	v_add_u32_e32 v140, s69, v167
	s_barrier
	ds_read_b128 v[128:131], v140
	ds_read_b128 v[132:135], v140 offset:1024
	ds_read_b128 v[136:139], v140 offset:2048
	ds_read_b128 v[140:143], v140 offset:3072
	s_add_u32 s40, s40, 0x160000
	s_addc_u32 s41, s41, 0
	s_mov_b32 m0, s49
	v_lshl_add_u64 v[196:197], s[40:41], 0, v[146:147]
	ds_read_b128 v[156:159], v170 offset:32768
	ds_read_b128 v[160:163], v170 offset:33792
	ds_read_b128 v[172:175], v170 offset:34816
	ds_read_b128 v[176:179], v170 offset:35840
	ds_read_b128 v[180:183], v170 offset:36864
	ds_read_b128 v[184:187], v170 offset:37888
	ds_read_b128 v[188:191], v170 offset:38912
	ds_read_b128 v[192:195], v170 offset:39936
	global_load_lds_dwordx4 v[196:197], off
	v_lshl_add_u64 v[196:197], s[40:41], 0, v[148:149]
	s_mov_b32 m0, s50
	s_nop 0
	global_load_lds_dwordx4 v[196:197], off
	s_waitcnt lgkmcnt(8)
	s_barrier
	s_waitcnt lgkmcnt(0)
	s_setprio 1
	s_waitcnt lgkmcnt(0)
	v_mfma_f32_16x16x32_bf16 v[124:127], v[128:131], v[156:159], v[124:127]
	v_mfma_f32_16x16x32_bf16 v[120:123], v[136:139], v[156:159], v[120:123]
	v_mfma_f32_16x16x32_bf16 v[116:119], v[128:131], v[172:175], v[116:119]
	v_mfma_f32_16x16x32_bf16 v[104:107], v[136:139], v[172:175], v[104:107]
	v_mfma_f32_16x16x32_bf16 v[92:95], v[128:131], v[180:183], v[92:95]
	v_mfma_f32_16x16x32_bf16 v[88:91], v[136:139], v[180:183], v[88:91]
	v_mfma_f32_16x16x32_bf16 v[76:79], v[128:131], v[188:191], v[76:79]
	v_mfma_f32_16x16x32_bf16 v[72:75], v[136:139], v[188:191], v[72:75]
	v_mfma_f32_16x16x32_bf16 v[124:127], v[132:135], v[160:163], v[124:127]
	v_mfma_f32_16x16x32_bf16 v[120:123], v[140:143], v[160:163], v[120:123]
	v_mfma_f32_16x16x32_bf16 v[116:119], v[132:135], v[176:179], v[116:119]
	v_mfma_f32_16x16x32_bf16 v[104:107], v[140:143], v[176:179], v[104:107]
	v_mfma_f32_16x16x32_bf16 v[92:95], v[132:135], v[184:187], v[92:95]
	v_mfma_f32_16x16x32_bf16 v[88:91], v[140:143], v[184:187], v[88:91]
	v_mfma_f32_16x16x32_bf16 v[76:79], v[132:135], v[192:195], v[76:79]
	v_mfma_f32_16x16x32_bf16 v[72:75], v[140:143], v[192:195], v[72:75]
	s_setprio 0
	s_barrier
	s_add_i32 s40, 0, 0x1c000
	s_add_i32 s41, s69, s46
	v_add_u32_e32 v208, s40, v167
	v_lshl_add_u64 v[164:165], v[164:165], 0, s[10:11]
	s_mov_b32 m0, s41
	ds_read_b128 v[196:199], v208
	ds_read_b128 v[200:203], v208 offset:1024
	ds_read_b128 v[204:207], v208 offset:2048
	ds_read_b128 v[208:211], v208 offset:3072
	global_load_lds_dwordx4 v[164:165], off
	v_lshl_add_u64 v[164:165], v[212:213], 0, s[10:11]
	s_add_i32 m0, s41, 0x2000
	s_nop 0
	global_load_lds_dwordx4 v[164:165], off
	s_barrier
	s_waitcnt lgkmcnt(0)
	s_setprio 1
	s_waitcnt lgkmcnt(0)
	v_mfma_f32_16x16x32_bf16 v[112:115], v[196:199], v[156:159], v[112:115]
	v_mfma_f32_16x16x32_bf16 v[108:111], v[204:207], v[156:159], v[108:111]
	v_mfma_f32_16x16x32_bf16 v[100:103], v[196:199], v[172:175], v[100:103]
	v_mfma_f32_16x16x32_bf16 v[96:99], v[204:207], v[172:175], v[96:99]
	v_mfma_f32_16x16x32_bf16 v[84:87], v[196:199], v[180:183], v[84:87]
	v_mfma_f32_16x16x32_bf16 v[80:83], v[204:207], v[180:183], v[80:83]
	v_mfma_f32_16x16x32_bf16 v[68:71], v[196:199], v[188:191], v[68:71]
	v_mfma_f32_16x16x32_bf16 v[64:67], v[204:207], v[188:191], v[64:67]
	v_mfma_f32_16x16x32_bf16 v[112:115], v[200:203], v[160:163], v[112:115]
	v_mfma_f32_16x16x32_bf16 v[108:111], v[208:211], v[160:163], v[108:111]
	v_mfma_f32_16x16x32_bf16 v[100:103], v[200:203], v[176:179], v[100:103]
	v_mfma_f32_16x16x32_bf16 v[96:99], v[208:211], v[176:179], v[96:99]
	v_mfma_f32_16x16x32_bf16 v[84:87], v[200:203], v[184:187], v[84:87]
	v_mfma_f32_16x16x32_bf16 v[80:83], v[208:211], v[184:187], v[80:83]
	v_mfma_f32_16x16x32_bf16 v[68:71], v[200:203], v[192:195], v[68:71]
	v_mfma_f32_16x16x32_bf16 v[64:67], v[208:211], v[192:195], v[64:67]
	s_setprio 0
	s_mov_b32 m0, s54
	v_lshl_add_u64 v[164:165], v[214:215], 0, s[10:11]
	s_barrier
	ds_read_b128 v[156:159], v170 offset:49152
	ds_read_b128 v[160:163], v170 offset:50176
	ds_read_b128 v[172:175], v170 offset:51200
	ds_read_b128 v[176:179], v170 offset:52224
	ds_read_b128 v[180:183], v170 offset:53248
	ds_read_b128 v[184:187], v170 offset:54272
	ds_read_b128 v[188:191], v170 offset:55296
	ds_read_b128 v[192:195], v170 offset:56320
	global_load_lds_dwordx4 v[164:165], off
	v_lshl_add_u64 v[164:165], v[216:217], 0, s[10:11]
	s_mov_b32 m0, s55
	s_nop 0
	global_load_lds_dwordx4 v[164:165], off
	s_barrier
	s_waitcnt lgkmcnt(0)
	s_setprio 1
	s_waitcnt lgkmcnt(0)
	v_mfma_f32_16x16x32_bf16 v[60:63], v[128:131], v[156:159], v[60:63]
	v_mfma_f32_16x16x32_bf16 v[56:59], v[136:139], v[156:159], v[56:59]
	v_mfma_f32_16x16x32_bf16 v[44:47], v[128:131], v[172:175], v[44:47]
	v_mfma_f32_16x16x32_bf16 v[40:43], v[136:139], v[172:175], v[40:43]
	v_mfma_f32_16x16x32_bf16 v[36:39], v[128:131], v[180:183], v[36:39]
	v_mfma_f32_16x16x32_bf16 v[28:31], v[136:139], v[180:183], v[28:31]
	v_mfma_f32_16x16x32_bf16 v[20:23], v[128:131], v[188:191], v[20:23]
	v_mfma_f32_16x16x32_bf16 v[12:15], v[136:139], v[188:191], v[12:15]
	v_mfma_f32_16x16x32_bf16 v[60:63], v[132:135], v[160:163], v[60:63]
	v_mfma_f32_16x16x32_bf16 v[56:59], v[140:143], v[160:163], v[56:59]
	v_mfma_f32_16x16x32_bf16 v[44:47], v[132:135], v[176:179], v[44:47]
	v_mfma_f32_16x16x32_bf16 v[40:43], v[140:143], v[176:179], v[40:43]
	v_mfma_f32_16x16x32_bf16 v[36:39], v[132:135], v[184:187], v[36:39]
	v_mfma_f32_16x16x32_bf16 v[28:31], v[140:143], v[184:187], v[28:31]
	v_mfma_f32_16x16x32_bf16 v[20:23], v[132:135], v[192:195], v[20:23]
	v_mfma_f32_16x16x32_bf16 v[12:15], v[140:143], v[192:195], v[12:15]
	s_setprio 0
	s_barrier
	s_add_u32 s38, s38, 0x160080
	s_addc_u32 s39, s39, 0
	s_add_i32 s40, s40, s46
	v_lshl_add_u64 v[128:129], s[38:39], 0, v[146:147]
	s_mov_b32 m0, s40
	s_nop 0
	global_load_lds_dwordx4 v[128:129], off
	v_lshl_add_u64 v[128:129], s[38:39], 0, v[148:149]
	s_add_i32 m0, s40, 0x2000
	s_nop 0
	global_load_lds_dwordx4 v[128:129], off
	s_waitcnt vmcnt(6)
	s_barrier
	s_setprio 1
	v_mfma_f32_16x16x32_bf16 v[52:55], v[196:199], v[156:159], v[52:55]
	v_mfma_f32_16x16x32_bf16 v[48:51], v[204:207], v[156:159], v[48:51]
	v_mfma_f32_16x16x32_bf16 v[32:35], v[196:199], v[172:175], v[32:35]
	v_mfma_f32_16x16x32_bf16 v[24:27], v[204:207], v[172:175], v[24:27]
	v_mfma_f32_16x16x32_bf16 v[16:19], v[196:199], v[180:183], v[16:19]
	v_mfma_f32_16x16x32_bf16 v[8:11], v[204:207], v[180:183], v[8:11]
	v_mfma_f32_16x16x32_bf16 v[4:7], v[196:199], v[188:191], v[4:7]
	v_mfma_f32_16x16x32_bf16 v[0:3], v[204:207], v[188:191], v[0:3]
	v_mfma_f32_16x16x32_bf16 v[52:55], v[200:203], v[160:163], v[52:55]
	v_mfma_f32_16x16x32_bf16 v[48:51], v[208:211], v[160:163], v[48:51]
	v_mfma_f32_16x16x32_bf16 v[32:35], v[200:203], v[176:179], v[32:35]
	v_mfma_f32_16x16x32_bf16 v[24:27], v[208:211], v[176:179], v[24:27]
	v_mfma_f32_16x16x32_bf16 v[16:19], v[200:203], v[184:187], v[16:19]
	v_mfma_f32_16x16x32_bf16 v[8:11], v[208:211], v[184:187], v[8:11]
	v_mfma_f32_16x16x32_bf16 v[4:7], v[200:203], v[192:195], v[4:7]
	v_mfma_f32_16x16x32_bf16 v[0:3], v[208:211], v[192:195], v[0:3]
	s_setprio 0
	s_add_i32 s68, s68, 2
	s_add_u32 s36, s36, 0x100
	s_addc_u32 s37, s37, 0
	s_add_u32 s28, s28, 0x100
	s_addc_u32 s29, s29, 0
	s_cmpk_gt_u32 s68, 0x55
	s_barrier
	s_cbranch_scc0 .LBB0_1285
